# M17 + one static s_setprio 1 for waves 4-7 around the attention KV loop
# speedup vs baseline: 1.0042x; 1.0042x over previous
.LBB0_801:
	s_and_b64 vcc, exec, s[6:7]
	s_cbranch_vccz .LBB0_779
	v_mov_b32_e32 v175, v0
	s_cmp_lg_u32 0, -1
	v_ashrrev_i32_e32 v172, 6, v175
	v_and_b32_e32 v173, 31, v175
	v_lshl_or_b32 v35, v172, 5, v173
	v_lshlrev_b32_e32 v2, 3, v35
	v_ashrrev_i32_e32 v3, 31, v2
	v_lshl_add_u64 v[2:3], v[2:3], 2, s[22:23]
	global_load_dwordx4 v[36:39], v[2:3], off
	global_load_dwordx4 v[40:43], v[2:3], off offset:16
	v_bfe_u32 v174, v175, 5, 1
	v_mul_lo_u32 v2, v35, s56
	v_lshl_or_b32 v114, v174, 3, v2
	v_lshl_add_u64 v[6:7], v[114:115], 1, s[20:21]
	global_load_dwordx4 v[44:47], v[6:7], off
	global_load_dwordx4 v[48:51], v[6:7], off offset:32
	global_load_dwordx4 v[52:55], v[6:7], off offset:64
	global_load_dwordx4 v[56:59], v[6:7], off offset:96
	global_load_dwordx4 v[30:33], v[6:7], off offset:128
	global_load_dwordx4 v[26:29], v[6:7], off offset:160
	global_load_dwordx4 v[22:25], v[6:7], off offset:192
	global_load_dwordx4 v[18:21], v[6:7], off offset:224
	global_load_dwordx4 v[10:13], v[6:7], off offset:256
	global_load_dwordx4 v[2:5], v[6:7], off offset:288
	global_load_dwordx4 v[14:17], v[6:7], off offset:320
	s_nop 0
	global_load_dwordx4 v[6:9], v[6:7], off offset:352
	v_and_b32_e32 v114, 32, v175
	v_mov_b32_e32 v180, 0
	s_waitcnt vmcnt(11)
	v_and_b32_e32 v77, 0xffff0000, v44
	v_lshlrev_b32_e32 v76, 16, v44
	v_mul_f32_e32 v44, v77, v77
	v_lshlrev_b32_e32 v78, 16, v45
	v_fmac_f32_e32 v44, v76, v76
	v_and_b32_e32 v79, 0xffff0000, v45
	v_fmac_f32_e32 v44, v78, v78
	v_lshlrev_b32_e32 v80, 16, v46
	v_fmac_f32_e32 v44, v79, v79
	v_and_b32_e32 v81, 0xffff0000, v46
	v_fmac_f32_e32 v44, v80, v80
	v_lshlrev_b32_e32 v82, 16, v47
	v_fmac_f32_e32 v44, v81, v81
	v_and_b32_e32 v83, 0xffff0000, v47
	v_fmac_f32_e32 v44, v82, v82
	s_waitcnt vmcnt(10)
	v_lshlrev_b32_e32 v84, 16, v48
	v_fmac_f32_e32 v44, v83, v83
	v_and_b32_e32 v85, 0xffff0000, v48
	v_fmac_f32_e32 v44, v84, v84
	v_lshlrev_b32_e32 v86, 16, v49
	v_fmac_f32_e32 v44, v85, v85
	v_and_b32_e32 v87, 0xffff0000, v49
	v_fmac_f32_e32 v44, v86, v86
	v_lshlrev_b32_e32 v88, 16, v50
	v_fmac_f32_e32 v44, v87, v87
	v_and_b32_e32 v89, 0xffff0000, v50
	v_fmac_f32_e32 v44, v88, v88
	v_lshlrev_b32_e32 v90, 16, v51
	v_fmac_f32_e32 v44, v89, v89
	v_and_b32_e32 v91, 0xffff0000, v51
	v_fmac_f32_e32 v44, v90, v90
	s_waitcnt vmcnt(9)
	v_lshlrev_b32_e32 v92, 16, v52
	v_fmac_f32_e32 v44, v91, v91
	v_and_b32_e32 v93, 0xffff0000, v52
	v_fmac_f32_e32 v44, v92, v92
	v_lshlrev_b32_e32 v94, 16, v53
	v_fmac_f32_e32 v44, v93, v93
	v_and_b32_e32 v95, 0xffff0000, v53
	v_fmac_f32_e32 v44, v94, v94
	v_lshlrev_b32_e32 v96, 16, v54
	v_fmac_f32_e32 v44, v95, v95
	v_and_b32_e32 v97, 0xffff0000, v54
	v_fmac_f32_e32 v44, v96, v96
	v_lshlrev_b32_e32 v98, 16, v55
	v_fmac_f32_e32 v44, v97, v97
	v_and_b32_e32 v99, 0xffff0000, v55
	v_fmac_f32_e32 v44, v98, v98
	s_waitcnt vmcnt(8)
	v_lshlrev_b32_e32 v100, 16, v56
	v_fmac_f32_e32 v44, v99, v99
	v_and_b32_e32 v101, 0xffff0000, v56
	v_fmac_f32_e32 v44, v100, v100
	v_lshlrev_b32_e32 v102, 16, v57
	v_fmac_f32_e32 v44, v101, v101
	v_and_b32_e32 v103, 0xffff0000, v57
	v_fmac_f32_e32 v44, v102, v102
	v_lshlrev_b32_e32 v104, 16, v58
	v_fmac_f32_e32 v44, v103, v103
	v_and_b32_e32 v105, 0xffff0000, v58
	v_fmac_f32_e32 v44, v104, v104
	v_lshlrev_b32_e32 v106, 16, v59
	v_fmac_f32_e32 v44, v105, v105
	v_and_b32_e32 v107, 0xffff0000, v59
	v_fmac_f32_e32 v44, v106, v106
	s_waitcnt vmcnt(7)
	v_lshlrev_b32_e32 v108, 16, v30
	v_fmac_f32_e32 v44, v107, v107
	v_and_b32_e32 v109, 0xffff0000, v30
	v_fmac_f32_e32 v44, v108, v108
	v_lshlrev_b32_e32 v110, 16, v31
	v_fmac_f32_e32 v44, v109, v109
	v_mov_b32_e32 v60, v36
	v_mov_b32_e32 v61, v40
	v_mov_b32_e32 v40, v37
	v_mov_b32_e32 v36, v38
	v_mov_b32_e32 v37, v42
	v_mov_b32_e32 v42, v39
	v_fmac_f32_e32 v44, v110, v110
	v_and_b32_e32 v31, 0xffff0000, v31
	v_pk_add_f32 v[38:39], v[60:61], v[40:41]
	v_pk_add_f32 v[36:37], v[36:37], v[42:43]
	v_fmac_f32_e32 v44, v31, v31
	v_lshlrev_b32_e32 v111, 16, v32
	v_pk_add_f32 v[36:37], v[38:39], v[36:37]
	v_fmac_f32_e32 v44, v111, v111
	v_and_b32_e32 v112, 0xffff0000, v32
	v_add_f32_e32 v30, v36, v37
	v_fmac_f32_e32 v44, v112, v112
	v_lshlrev_b32_e32 v113, 16, v33
	v_fmamk_f32 v30, v30, 0x3b000000, v1
	v_fmac_f32_e32 v44, v113, v113
	v_and_b32_e32 v33, 0xffff0000, v33
	v_mul_f32_e32 v34, 0x4f800000, v30
	v_cmp_gt_f32_e32 vcc, s70, v30
	v_fmac_f32_e32 v44, v33, v33
	s_waitcnt vmcnt(6)
	v_lshlrev_b32_e32 v136, 16, v26
	v_cndmask_b32_e32 v30, v30, v34, vcc
	v_fmac_f32_e32 v44, v136, v136
	v_and_b32_e32 v137, 0xffff0000, v26
	v_sqrt_f32_e32 v34, v30
	v_fmac_f32_e32 v44, v137, v137
	v_lshlrev_b32_e32 v138, 16, v27
	v_fmac_f32_e32 v44, v138, v138
	v_and_b32_e32 v27, 0xffff0000, v27
	v_fmac_f32_e32 v44, v27, v27
	v_lshlrev_b32_e32 v139, 16, v28
	v_fmac_f32_e32 v44, v139, v139
	v_and_b32_e32 v140, 0xffff0000, v28
	v_add_u32_e32 v36, -1, v34
	v_fmac_f32_e32 v44, v140, v140
	v_lshlrev_b32_e32 v141, 16, v29
	v_add_u32_e32 v37, 1, v34
	v_fma_f32 v38, -v36, v34, v30
	v_fmac_f32_e32 v44, v141, v141
	v_and_b32_e32 v29, 0xffff0000, v29
	v_fma_f32 v39, -v37, v34, v30
	v_cmp_ge_f32_e64 s[36:37], 0, v38
	v_fmac_f32_e32 v44, v29, v29
	s_waitcnt vmcnt(5)
	v_lshlrev_b32_e32 v142, 16, v22
	v_cndmask_b32_e64 v34, v34, v36, s[36:37]
	v_cmp_lt_f32_e64 s[36:37], 0, v39
	v_fmac_f32_e32 v44, v142, v142
	v_and_b32_e32 v143, 0xffff0000, v22
	v_cndmask_b32_e64 v34, v34, v37, s[36:37]
	v_fmac_f32_e32 v44, v143, v143
	v_lshlrev_b32_e32 v144, 16, v23
	v_mul_f32_e32 v36, 0x37800000, v34
	v_fmac_f32_e32 v44, v144, v144
	v_and_b32_e32 v145, 0xffff0000, v23
	v_cndmask_b32_e32 v34, v34, v36, vcc
	v_cmp_class_f32_e32 vcc, v30, v226
	v_fmac_f32_e32 v44, v145, v145
	v_lshlrev_b32_e32 v146, 16, v24
	v_cndmask_b32_e32 v37, v34, v30, vcc
	v_fmac_f32_e32 v44, v146, v146
	v_and_b32_e32 v147, 0xffff0000, v24
	v_fmac_f32_e32 v44, v147, v147
	v_lshlrev_b32_e32 v148, 16, v25
	s_waitcnt vmcnt(2)
	v_lshlrev_b32_e32 v36, 16, v3
	v_and_b32_e32 v34, 0xffff0000, v3
	v_div_scale_f32 v3, s[6:7], v37, v37, 1.0
	global_load_dwordx4 v[50:53], v114, s[44:45] offset:16
	global_load_dwordx4 v[54:57], v114, s[44:45]
	v_fmac_f32_e32 v44, v148, v148
	v_and_b32_e32 v149, 0xffff0000, v25
	s_waitcnt vmcnt(2)
	v_and_b32_e32 v39, 0xffff0000, v7
	v_lshlrev_b32_e32 v38, 16, v7
	v_rcp_f32_e32 v7, v3
	v_fmac_f32_e32 v44, v149, v149
	v_lshlrev_b32_e32 v150, 16, v18
	v_fmac_f32_e32 v44, v150, v150
	v_and_b32_e32 v151, 0xffff0000, v18
	v_fmac_f32_e32 v44, v151, v151
	v_lshlrev_b32_e32 v152, 16, v19
	v_fmac_f32_e32 v44, v152, v152
	v_and_b32_e32 v153, 0xffff0000, v19
	v_lshlrev_b32_e32 v32, 16, v4
	v_and_b32_e32 v30, 0xffff0000, v4
	v_fma_f32 v4, -v3, v7, 1.0
	v_fmac_f32_e32 v44, v153, v153
	v_lshlrev_b32_e32 v154, 16, v20
	v_fmac_f32_e32 v7, v4, v7
	v_div_scale_f32 v4, vcc, 1.0, v37, 1.0
	v_fmac_f32_e32 v44, v154, v154
	v_and_b32_e32 v155, 0xffff0000, v20
	v_mul_f32_e32 v116, v4, v7
	v_fmac_f32_e32 v44, v155, v155
	v_lshlrev_b32_e32 v156, 16, v21
	v_lshlrev_b32_e32 v28, 16, v5
	v_and_b32_e32 v26, 0xffff0000, v5
	v_fma_f32 v5, -v3, v116, v4
	v_fmac_f32_e32 v44, v156, v156
	v_and_b32_e32 v157, 0xffff0000, v21
	v_fmac_f32_e32 v116, v5, v7
	v_lshlrev_b32_e32 v23, 16, v14
	v_lshlrev_b32_e32 v22, 16, v10
	v_fmac_f32_e32 v44, v157, v157
	v_and_b32_e32 v41, 0xffff0000, v8
	v_lshlrev_b32_e32 v40, 16, v8
	v_fma_f32 v117, -v3, v116, v4
	v_lshlrev_b32_e32 v8, 16, v13
	v_and_b32_e32 v4, 0xffff0000, v13
	v_lshlrev_b32_e32 v19, 16, v16
	v_and_b32_e32 v13, 0xffff0000, v16
	v_lshlrev_b32_e32 v20, 16, v11
	v_and_b32_e32 v16, 0xffff0000, v11
	v_pk_mul_f32 v[72:73], v[22:23], v[22:23]
	v_and_b32_e32 v11, 0xffff0000, v14
	v_and_b32_e32 v10, 0xffff0000, v10
	v_and_b32_e32 v43, 0xffff0000, v9
	v_lshlrev_b32_e32 v42, 16, v9
	v_lshlrev_b32_e32 v9, 16, v17
	v_and_b32_e32 v5, 0xffff0000, v17
	v_lshlrev_b32_e32 v21, 16, v15
	v_and_b32_e32 v17, 0xffff0000, v15
	v_add_f32_e32 v3, v72, v44
	v_pk_mul_f32 v[14:15], v[10:11], v[10:11]
	v_pk_mul_f32 v[68:69], v[20:21], v[20:21]
	v_add_f32_e32 v3, v14, v3
	v_lshlrev_b32_e32 v18, 16, v12
	v_pk_mul_f32 v[70:71], v[16:17], v[16:17]
	v_add_f32_e32 v3, v68, v3
	v_pk_mul_f32 v[64:65], v[18:19], v[18:19]
	v_and_b32_e32 v12, 0xffff0000, v12
	v_add_f32_e32 v3, v70, v3
	v_pk_mul_f32 v[66:67], v[12:13], v[12:13]
	v_add_f32_e32 v3, v64, v3
	v_pk_mul_f32 v[60:61], v[8:9], v[8:9]
	v_add_f32_e32 v3, v66, v3
	v_pk_mul_f32 v[62:63], v[4:5], v[4:5]
	v_add_f32_e32 v3, v60, v3
	v_lshlrev_b32_e32 v45, 16, v6
	v_lshlrev_b32_e32 v44, 16, v2
	v_add_f32_e32 v3, v62, v3
	v_pk_mul_f32 v[74:75], v[44:45], v[44:45]
	v_and_b32_e32 v47, 0xffff0000, v6
	v_and_b32_e32 v46, 0xffff0000, v2
	v_add_f32_e32 v14, v74, v3
	v_pk_mul_f32 v[2:3], v[46:47], v[46:47]
	v_pk_mul_f32 v[24:25], v[38:39], v[38:39]
	v_add_f32_e32 v2, v2, v14
	v_fmac_f32_e32 v2, v36, v36
	v_fmac_f32_e32 v2, v34, v34
	v_fmac_f32_e32 v2, v32, v32
	v_fmac_f32_e32 v2, v30, v30
	v_fmac_f32_e32 v2, v28, v28
	v_fmac_f32_e32 v2, v26, v26
	v_add_f32_e32 v2, v73, v2
	v_add_f32_e32 v2, v15, v2
	v_add_f32_e32 v2, v69, v2
	v_add_f32_e32 v2, v71, v2
	v_add_f32_e32 v2, v65, v2
	v_add_f32_e32 v2, v67, v2
	v_add_f32_e32 v2, v61, v2
	v_add_f32_e32 v2, v63, v2
	v_add_f32_e32 v2, v75, v2
	v_add_f32_e32 v2, v3, v2
	v_add_f32_e32 v2, v24, v2
	v_pk_mul_f32 v[48:49], v[40:41], v[40:41]
	v_add_f32_e32 v2, v25, v2
	v_add_f32_e32 v2, v48, v2
	v_pk_mul_f32 v[58:59], v[42:43], v[42:43]
	v_add_f32_e32 v2, v49, v2
	v_add_f32_e32 v2, v58, v2
	v_add_f32_e32 v2, v59, v2
	ds_bpermute_b32 v3, v189, v2
	v_div_fmas_f32 v6, v117, v7, v116
	v_div_fixup_f32 v6, v6, v37, 1.0
	v_mul_f32_e32 v7, v6, v6
	v_mul_f32_e32 v6, 0x3dd53b94, v6
	s_waitcnt lgkmcnt(0)
	v_add_f32_e32 v2, v2, v3
	v_mul_f32_e32 v2, v7, v2
	v_fmamk_f32 v2, v2, 0x3baaaaab, v1
	v_mul_f32_e32 v3, 0x4f800000, v2
	v_cmp_gt_f32_e32 vcc, s70, v2
	s_nop 1
	v_cndmask_b32_e32 v2, v2, v3, vcc
	v_sqrt_f32_e32 v3, v2
	s_nop 0
	v_add_u32_e32 v7, -1, v3
	v_fma_f32 v14, -v7, v3, v2
	v_cmp_ge_f32_e64 s[36:37], 0, v14
	v_add_u32_e32 v14, 1, v3
	s_nop 0
	v_cndmask_b32_e64 v7, v3, v7, s[36:37]
	v_fma_f32 v3, -v14, v3, v2
	v_cmp_lt_f32_e64 s[36:37], 0, v3
	s_nop 1
	v_cndmask_b32_e64 v3, v7, v14, s[36:37]
	v_mul_f32_e32 v7, 0x37800000, v3
	v_cndmask_b32_e32 v3, v3, v7, vcc
	v_cmp_class_f32_e32 vcc, v2, v226
	s_nop 1
	v_cndmask_b32_e32 v2, v3, v2, vcc
	v_div_scale_f32 v3, s[6:7], v2, v2, v6
	v_rcp_f32_e32 v7, v3
	s_nop 0
	v_fma_f32 v14, -v3, v7, 1.0
	v_fmac_f32_e32 v7, v14, v7
	v_div_scale_f32 v14, vcc, v6, v2, v6
	v_mul_f32_e32 v15, v14, v7
	v_fma_f32 v24, -v3, v15, v14
	v_fmac_f32_e32 v15, v24, v7
	v_fma_f32 v3, -v3, v15, v14
	v_div_fmas_f32 v3, v3, v7, v15
	v_div_fixup_f32 v48, v3, v2, v6
	v_mul_f32_e32 v2, v48, v76
	v_mul_f32_e32 v3, v48, v77
	s_waitcnt vmcnt(0)
	v_mul_f32_e32 v2, v54, v2
	v_mul_f32_e32 v3, v55, v3
	v_cvt_pk_bf16_f32 v116, v2, v3
	v_mul_f32_e32 v2, v48, v78
	v_mul_f32_e32 v3, v48, v79
	v_mul_f32_e32 v2, v56, v2
	v_mul_f32_e32 v3, v57, v3
	v_cvt_pk_bf16_f32 v117, v2, v3
	v_mul_f32_e32 v2, v48, v80
	v_mul_f32_e32 v3, v48, v81
	v_mul_f32_e32 v2, v50, v2
	v_mul_f32_e32 v3, v51, v3
	v_cvt_pk_bf16_f32 v118, v2, v3
	v_mul_f32_e32 v2, v48, v82
	v_mul_f32_e32 v3, v48, v83
	v_mul_f32_e32 v2, v52, v2
	v_mul_f32_e32 v3, v53, v3
	v_cvt_pk_bf16_f32 v119, v2, v3
	global_load_dwordx4 v[50:53], v114, s[44:45] offset:64
	global_load_dwordx4 v[54:57], v114, s[44:45] offset:80
	v_mul_f32_e32 v2, v48, v84
	v_mul_f32_e32 v3, v48, v85
	v_mul_f32_e32 v6, v48, v94
	v_mul_f32_e32 v7, v48, v95
	v_mul_f32_e32 v14, v48, v96
	v_mul_f32_e32 v15, v48, v97
	v_mul_f32_e32 v24, v48, v98
	v_mul_f32_e32 v25, v48, v99
	v_pk_mul_f32 v[12:13], v[48:49], v[12:13] op_sel_hi:[0,1]
	v_pk_mul_f32 v[8:9], v[48:49], v[8:9] op_sel_hi:[0,1]
	v_pk_mul_f32 v[4:5], v[48:49], v[4:5] op_sel_hi:[0,1]
	s_waitcnt vmcnt(1)
	v_mul_f32_e32 v2, v50, v2
	v_mul_f32_e32 v3, v51, v3
	v_cvt_pk_bf16_f32 v120, v2, v3
	v_mul_f32_e32 v2, v48, v86
	v_mul_f32_e32 v3, v48, v87
	v_mul_f32_e32 v2, v52, v2
	v_mul_f32_e32 v3, v53, v3
	v_cvt_pk_bf16_f32 v121, v2, v3
	v_mul_f32_e32 v2, v48, v88
	v_mul_f32_e32 v3, v48, v89
	s_waitcnt vmcnt(0)
	v_mul_f32_e32 v2, v54, v2
	v_mul_f32_e32 v3, v55, v3
	v_cvt_pk_bf16_f32 v122, v2, v3
	v_mul_f32_e32 v2, v48, v90
	v_mul_f32_e32 v3, v48, v91
	v_mul_f32_e32 v2, v56, v2
	v_mul_f32_e32 v3, v57, v3
	v_cvt_pk_bf16_f32 v123, v2, v3
	global_load_dwordx4 v[50:53], v114, s[44:45] offset:128
	global_load_dwordx4 v[54:57], v114, s[44:45] offset:144
	v_mul_f32_e32 v2, v48, v92
	v_mul_f32_e32 v3, v48, v93
	s_waitcnt vmcnt(1)
	v_mul_f32_e32 v2, v50, v2
	v_mul_f32_e32 v3, v51, v3
	v_mul_f32_e32 v6, v52, v6
	v_mul_f32_e32 v7, v53, v7
	s_waitcnt vmcnt(0)
	v_mul_f32_e32 v14, v54, v14
	v_mul_f32_e32 v15, v55, v15
	v_mul_f32_e32 v24, v56, v24
	v_mul_f32_e32 v25, v57, v25
	v_cvt_pk_bf16_f32 v124, v2, v3
	v_cvt_pk_bf16_f32 v125, v6, v7
	v_cvt_pk_bf16_f32 v126, v14, v15
	v_cvt_pk_bf16_f32 v127, v24, v25
	global_load_dwordx4 v[50:53], v114, s[44:45] offset:192
	global_load_dwordx4 v[54:57], v114, s[44:45] offset:208
	v_mul_f32_e32 v2, v48, v100
	v_mul_f32_e32 v3, v48, v101
	v_mul_f32_e32 v6, v48, v102
	v_mul_f32_e32 v7, v48, v103
	v_mul_f32_e32 v14, v48, v104
	v_mul_f32_e32 v15, v48, v105
	v_mul_f32_e32 v24, v48, v106
	v_mul_f32_e32 v25, v48, v107
	s_waitcnt vmcnt(1)
	v_mul_f32_e32 v2, v50, v2
	v_mul_f32_e32 v3, v51, v3
	v_mul_f32_e32 v6, v52, v6
	v_mul_f32_e32 v7, v53, v7
	s_waitcnt vmcnt(0)
	v_mul_f32_e32 v14, v54, v14
	v_mul_f32_e32 v15, v55, v15
	v_mul_f32_e32 v24, v56, v24
	v_mul_f32_e32 v25, v57, v25
	v_cvt_pk_bf16_f32 v128, v2, v3
	v_cvt_pk_bf16_f32 v129, v6, v7
	v_cvt_pk_bf16_f32 v130, v14, v15
	v_cvt_pk_bf16_f32 v131, v24, v25
	global_load_dwordx4 v[50:53], v114, s[44:45] offset:256
	global_load_dwordx4 v[54:57], v114, s[44:45] offset:272
	v_mul_f32_e32 v2, v48, v108
	v_mul_f32_e32 v3, v48, v109
	v_mul_f32_e32 v6, v48, v110
	v_mul_f32_e32 v7, v48, v31
	v_mul_f32_e32 v14, v48, v111
	v_mul_f32_e32 v15, v48, v112
	v_mul_f32_e32 v24, v48, v113
	v_mul_f32_e32 v25, v48, v33
	v_add_u32_e32 v31, 0x200, v175
	v_add_u32_e32 v33, 0x400, v175
	v_lshlrev_b32_e32 v112, 4, v175
	s_waitcnt vmcnt(1)
	v_mul_f32_e32 v2, v50, v2
	v_mul_f32_e32 v3, v51, v3
	v_mul_f32_e32 v6, v52, v6
	v_mul_f32_e32 v7, v53, v7
	s_waitcnt vmcnt(0)
	v_mul_f32_e32 v14, v54, v14
	v_mul_f32_e32 v15, v55, v15
	v_mul_f32_e32 v24, v56, v24
	v_mul_f32_e32 v25, v57, v25
	v_cvt_pk_bf16_f32 v132, v2, v3
	v_cvt_pk_bf16_f32 v133, v6, v7
	v_cvt_pk_bf16_f32 v134, v14, v15
	v_cvt_pk_bf16_f32 v135, v24, v25
	global_load_dwordx4 v[50:53], v114, s[44:45] offset:320
	global_load_dwordx4 v[54:57], v114, s[44:45] offset:336
	v_mul_f32_e32 v2, v48, v136
	v_mul_f32_e32 v3, v48, v137
	v_mul_f32_e32 v6, v48, v138
	v_mul_f32_e32 v7, v48, v27
	v_mul_f32_e32 v14, v48, v139
	v_mul_f32_e32 v15, v48, v140
	v_mul_f32_e32 v24, v48, v141
	v_mul_f32_e32 v25, v48, v29
	v_lshrrev_b32_e32 v27, 3, v175
	v_mul_hi_i32 v29, v175, s59
	v_bitop3_b32 v27, v27, v174, 1 bitop3:0x6c
	s_waitcnt vmcnt(1)
	v_mul_f32_e32 v2, v50, v2
	v_mul_f32_e32 v3, v51, v3
	v_mul_f32_e32 v6, v52, v6
	v_mul_f32_e32 v7, v53, v7
	s_waitcnt vmcnt(0)
	v_mul_f32_e32 v14, v54, v14
	v_mul_f32_e32 v15, v55, v15
	v_mul_f32_e32 v24, v56, v24
	v_mul_f32_e32 v25, v57, v25
	v_cvt_pk_bf16_f32 v136, v2, v3
	v_cvt_pk_bf16_f32 v137, v6, v7
	v_cvt_pk_bf16_f32 v138, v14, v15
	v_cvt_pk_bf16_f32 v139, v24, v25
	global_load_dwordx4 v[50:53], v114, s[44:45] offset:384
	global_load_dwordx4 v[54:57], v114, s[44:45] offset:400
	v_mul_f32_e32 v2, v48, v142
	v_mul_f32_e32 v3, v48, v143
	v_mul_f32_e32 v6, v48, v144
	v_mul_f32_e32 v7, v48, v145
	v_mul_f32_e32 v14, v48, v146
	v_mul_f32_e32 v15, v48, v147
	v_mul_f32_e32 v24, v48, v148
	v_mul_f32_e32 v25, v48, v149
	s_waitcnt vmcnt(1)
	v_mul_f32_e32 v2, v50, v2
	v_mul_f32_e32 v3, v51, v3
	v_mul_f32_e32 v6, v52, v6
	v_mul_f32_e32 v7, v53, v7
	s_waitcnt vmcnt(0)
	v_mul_f32_e32 v14, v54, v14
	v_mul_f32_e32 v15, v55, v15
	v_mul_f32_e32 v24, v56, v24
	v_mul_f32_e32 v25, v57, v25
	v_cvt_pk_bf16_f32 v140, v2, v3
	v_cvt_pk_bf16_f32 v141, v6, v7
	v_cvt_pk_bf16_f32 v142, v14, v15
	v_cvt_pk_bf16_f32 v143, v24, v25
	global_load_dwordx4 v[52:55], v114, s[44:45] offset:448
	global_load_dwordx4 v[56:59], v114, s[44:45] offset:464
	v_lshlrev_b32_e32 v2, 6, v35
	v_ashrrev_i32_e32 v3, 31, v2
	v_lshl_add_u64 v[2:3], v[2:3], 2, s[0:1]
	v_lshl_add_u64 v[50:51], v[2:3], 0, v[114:115]
	v_mul_f32_e32 v2, v48, v150
	v_mul_f32_e32 v3, v48, v151
	v_mul_f32_e32 v6, v48, v152
	v_mul_f32_e32 v7, v48, v153
	v_mul_f32_e32 v14, v48, v154
	v_mul_f32_e32 v15, v48, v155
	v_mul_f32_e32 v24, v48, v156
	v_mul_f32_e32 v25, v48, v157
	v_lshlrev_b32_e32 v35, 5, v173
	s_cselect_b32 s1, 0, 0
	v_lshl_or_b32 v178, v27, 4, v35
	s_add_i32 s0, s1, 0x14b00
	v_lshl_add_u32 v37, v172, 12, s0
	v_add_u32_e32 v177, v37, v178
	s_cmp_lg_u32 s58, -1
	s_cselect_b32 s0, s58, 0
	v_add_u32_e32 v113, s0, v178
	s_add_u32 s6, s52, 0x50180
	s_addc_u32 s7, s53, 0
	s_add_u32 s8, s52, 0x50000
	s_addc_u32 s9, s53, 0
	s_mov_b32 s0, -1
	s_waitcnt vmcnt(1)
	v_mul_f32_e32 v2, v52, v2
	v_mul_f32_e32 v3, v53, v3
	v_mul_f32_e32 v6, v54, v6
	v_mul_f32_e32 v7, v55, v7
	s_waitcnt vmcnt(0)
	v_mul_f32_e32 v14, v56, v14
	v_mul_f32_e32 v15, v57, v15
	v_mul_f32_e32 v24, v58, v24
	v_mul_f32_e32 v25, v59, v25
	v_cvt_pk_bf16_f32 v144, v2, v3
	v_cvt_pk_bf16_f32 v145, v6, v7
	v_cvt_pk_bf16_f32 v146, v14, v15
	v_cvt_pk_bf16_f32 v147, v24, v25
	global_load_dwordx4 v[52:55], v114, s[44:45] offset:512
	global_load_dwordx4 v[56:59], v114, s[44:45] offset:640
	global_load_dwordx4 v[60:63], v[50:51], off
	global_load_dwordx4 v[64:67], v[50:51], off offset:128
	global_load_dwordx4 v[68:71], v114, s[44:45] offset:528
	global_load_dwordx4 v[72:75], v114, s[44:45] offset:656
	global_load_dwordx4 v[76:79], v[50:51], off offset:16
	global_load_dwordx4 v[80:83], v[50:51], off offset:144
	v_pk_mul_f32 v[2:3], v[48:49], v[22:23] op_sel_hi:[0,1]
	v_pk_mul_f32 v[6:7], v[48:49], v[10:11] op_sel_hi:[0,1]
	v_pk_mul_f32 v[10:11], v[48:49], v[20:21] op_sel_hi:[0,1]
	v_pk_mul_f32 v[14:15], v[48:49], v[16:17] op_sel_hi:[0,1]
	v_pk_mul_f32 v[16:17], v[48:49], v[18:19] op_sel_hi:[0,1]
	v_mov_b32_e32 v49, v115
	s_waitcnt vmcnt(7)
	v_mov_b32_e32 v18, v52
	s_waitcnt vmcnt(6)
	v_mov_b32_e32 v19, v56
	v_mov_b32_e32 v56, v53
	v_mov_b32_e32 v24, v54
	v_mov_b32_e32 v25, v58
	v_mov_b32_e32 v58, v55
	s_waitcnt vmcnt(3)
	v_mov_b32_e32 v54, v68
	s_waitcnt vmcnt(2)
	v_mov_b32_e32 v55, v72
	v_mov_b32_e32 v72, v69
	v_mov_b32_e32 v68, v70
	v_mov_b32_e32 v69, v74
	v_mov_b32_e32 v74, v71
	v_mov_b32_e32 v20, v60
	v_mov_b32_e32 v21, v64
	v_mov_b32_e32 v22, v64
	v_mov_b32_e32 v23, v60
	v_mov_b32_e32 v64, v61
	v_mov_b32_e32 v60, v65
	v_mov_b32_e32 v52, v62
	v_mov_b32_e32 v53, v66
	v_mov_b32_e32 v84, v66
	v_mov_b32_e32 v85, v62
	v_mov_b32_e32 v66, v63
	v_mov_b32_e32 v62, v67
	s_waitcnt vmcnt(1)
	v_mov_b32_e32 v86, v76
	s_waitcnt vmcnt(0)
	v_mov_b32_e32 v87, v80
	v_mov_b32_e32 v88, v80
	v_mov_b32_e32 v89, v76
	v_mov_b32_e32 v80, v77
	v_mov_b32_e32 v76, v81
	v_mov_b32_e32 v90, v78
	v_mov_b32_e32 v91, v82
	v_mov_b32_e32 v92, v82
	v_mov_b32_e32 v93, v78
	v_mov_b32_e32 v82, v79
	v_mov_b32_e32 v78, v83
	v_pk_mul_f32 v[2:3], v[18:19], v[2:3]
	v_pk_mul_f32 v[6:7], v[56:57], v[6:7]
	v_pk_mul_f32 v[10:11], v[24:25], v[10:11]
	v_pk_mul_f32 v[14:15], v[58:59], v[14:15]
	v_pk_mul_f32 v[16:17], v[54:55], v[16:17]
	v_pk_mul_f32 v[12:13], v[72:73], v[12:13]
	v_pk_mul_f32 v[8:9], v[68:69], v[8:9]
	v_pk_mul_f32 v[4:5], v[74:75], v[4:5]
	v_pk_mul_f32 v[18:19], v[20:21], v[2:3]
	v_pk_mul_f32 v[2:3], v[22:23], v[2:3]
	v_pk_mul_f32 v[20:21], v[64:65], v[6:7]
	v_pk_mul_f32 v[6:7], v[60:61], v[6:7]
	v_pk_mul_f32 v[22:23], v[52:53], v[10:11]
	v_pk_mul_f32 v[10:11], v[84:85], v[10:11]
	v_pk_mul_f32 v[24:25], v[66:67], v[14:15]
	v_pk_mul_f32 v[14:15], v[62:63], v[14:15]
	v_pk_mul_f32 v[52:53], v[86:87], v[16:17]
	v_pk_mul_f32 v[16:17], v[88:89], v[16:17]
	v_pk_mul_f32 v[54:55], v[80:81], v[12:13]
	v_pk_mul_f32 v[12:13], v[76:77], v[12:13]
	v_pk_mul_f32 v[56:57], v[90:91], v[8:9]
	v_pk_mul_f32 v[8:9], v[92:93], v[8:9]
	v_pk_mul_f32 v[58:59], v[82:83], v[4:5]
	v_pk_mul_f32 v[4:5], v[78:79], v[4:5]
	v_sub_f32_e32 v18, v18, v19
	v_add_f32_e32 v2, v2, v3
	v_sub_f32_e32 v3, v20, v21
	v_add_f32_e32 v6, v6, v7
	v_sub_f32_e32 v7, v22, v23
	v_add_f32_e32 v10, v10, v11
	v_sub_f32_e32 v11, v24, v25
	v_add_f32_e32 v19, v14, v15
	v_sub_f32_e32 v20, v52, v53
	v_add_f32_e32 v21, v16, v17
	v_sub_f32_e32 v16, v54, v55
	v_add_f32_e32 v12, v12, v13
	v_sub_f32_e32 v13, v56, v57
	v_add_f32_e32 v8, v8, v9
	v_sub_f32_e32 v9, v58, v59
	v_add_f32_e32 v4, v4, v5
	v_cvt_pk_bf16_f32 v14, v18, v3
	v_cvt_pk_bf16_f32 v15, v7, v11
	v_cvt_pk_bf16_f32 v16, v20, v16
	v_cvt_pk_bf16_f32 v17, v13, v9
	v_cvt_pk_bf16_f32 v22, v2, v6
	v_cvt_pk_bf16_f32 v23, v10, v19
	v_cvt_pk_bf16_f32 v24, v21, v12
	v_cvt_pk_bf16_f32 v25, v8, v4
	global_load_dwordx4 v[18:21], v114, s[44:45] offset:576
	global_load_dwordx4 v[10:13], v114, s[44:45] offset:704
	global_load_dwordx4 v[2:5], v[50:51], off offset:64
	global_load_dwordx4 v[6:9], v[50:51], off offset:192
	global_load_dwordx4 v[52:55], v114, s[44:45] offset:592
	global_load_dwordx4 v[56:59], v114, s[44:45] offset:720
	global_load_dwordx4 v[66:69], v[50:51], off offset:80
	global_load_dwordx4 v[70:73], v[50:51], off offset:208
	v_lshrrev_b32_e32 v50, 31, v29
	v_ashrrev_i32_e32 v29, 2, v29
	v_mul_hi_i32 v51, v31, s59
	v_mul_hi_i32 v60, v33, s59
	v_add_u32_e32 v84, v29, v50
	v_lshrrev_b32_e32 v27, 31, v51
	v_ashrrev_i32_e32 v29, 2, v51
	v_lshrrev_b32_e32 v35, 31, v60
	v_ashrrev_i32_e32 v50, 2, v60
	v_add_u32_e32 v85, v29, v27
	v_add_u32_e32 v86, v50, v35
	v_ashrrev_i32_e32 v82, 4, v175
	v_lshlrev_b32_e32 v83, 3, v175
	v_mul_lo_u32 v51, v84, 24
	v_mul_lo_u32 v29, v85, 24
	v_mul_lo_u32 v50, v86, 24
	v_and_b32_e32 v76, 0x78, v83
	v_mul_lo_u32 v77, v82, s57
	v_mul_lo_u32 v37, v84, s57
	v_sub_u32_e32 v87, v175, v51
	v_mul_lo_u32 v27, v85, s57
	v_mul_lo_u32 v35, v86, s57
	v_sub_u32_e32 v88, v31, v29
	v_sub_u32_e32 v89, v33, v50
	v_lshl_add_u32 v60, v87, 3, v37
	v_lshl_add_u32 v64, v88, 3, v27
	v_lshl_add_u32 v74, v89, 3, v35
	v_mov_b32_e32 v37, v38
	v_mov_b32_e32 v35, v39
	v_mov_b32_e32 v33, v40
	v_mov_b32_e32 v31, v41
	v_mov_b32_e32 v29, v42
	v_mov_b32_e32 v27, v43
	v_or_b32_e32 v114, v77, v76
	v_pk_mul_f32 v[38:39], v[48:49], v[44:45] op_sel_hi:[0,1]
	v_pk_mul_f32 v[40:41], v[48:49], v[46:47] op_sel_hi:[0,1]
	v_pk_mul_f32 v[36:37], v[48:49], v[36:37] op_sel_hi:[0,1]
	v_pk_mul_f32 v[34:35], v[48:49], v[34:35] op_sel_hi:[0,1]
	v_pk_mul_f32 v[32:33], v[48:49], v[32:33] op_sel_hi:[0,1]
	v_pk_mul_f32 v[30:31], v[48:49], v[30:31] op_sel_hi:[0,1]
	v_pk_mul_f32 v[28:29], v[48:49], v[28:29] op_sel_hi:[0,1]
	v_pk_mul_f32 v[26:27], v[48:49], v[26:27] op_sel_hi:[0,1]
	ds_write_b128 v177, v[14:17]
	ds_write_b128 v177, v[22:25] offset:2048
	v_add_u32_e32 v48, 0x14000, v114
	v_lshlrev_b64 v[102:103], 1, v[48:49]
	v_mov_b32_e32 v61, v115
	v_mov_b32_e32 v65, v115
	v_mov_b32_e32 v75, v115
	v_lshlrev_b64 v[100:101], 1, v[114:115]
	v_lshlrev_b64 v[62:63], 1, v[60:61]
	v_lshlrev_b64 v[64:65], 1, v[64:65]
	v_lshlrev_b64 v[98:99], 1, v[74:75]
	v_lshl_add_u64 v[14:15], s[52:53], 0, v[100:101]
	v_lshl_add_u64 v[16:17], s[52:53], 0, v[102:103]
	v_lshl_add_u64 v[50:51], s[52:53], 0, v[62:63]
	v_lshl_add_u64 v[60:61], s[52:53], 0, v[64:65]
	v_lshl_add_u64 v[74:75], s[52:53], 0, v[98:99]
	v_and_b32_e32 v114, 63, v175
	v_lshlrev_b32_e32 v160, 3, v114
	s_waitcnt vmcnt(7)
	v_mov_b32_e32 v22, v18
	s_waitcnt vmcnt(6)
	v_mov_b32_e32 v23, v10
	v_mov_b32_e32 v10, v19
	v_mov_b32_e32 v18, v20
	v_mov_b32_e32 v19, v12
	v_mov_b32_e32 v12, v21
	s_waitcnt vmcnt(3)
	v_mov_b32_e32 v20, v52
	s_waitcnt vmcnt(2)
	v_mov_b32_e32 v21, v56
	v_mov_b32_e32 v56, v53
	v_mov_b32_e32 v52, v54
	v_mov_b32_e32 v53, v58
	v_mov_b32_e32 v58, v55
	v_mov_b32_e32 v24, v2
	v_mov_b32_e32 v25, v6
	v_mov_b32_e32 v42, v6
	v_mov_b32_e32 v43, v2
	v_mov_b32_e32 v6, v3
	v_mov_b32_e32 v2, v7
	v_mov_b32_e32 v44, v4
	v_mov_b32_e32 v45, v8
	v_mov_b32_e32 v46, v8
	v_mov_b32_e32 v47, v4
	v_mov_b32_e32 v8, v5
	v_mov_b32_e32 v4, v9
	s_waitcnt vmcnt(1)
	v_mov_b32_e32 v48, v66
	s_waitcnt vmcnt(0)
	v_mov_b32_e32 v49, v70
	v_mov_b32_e32 v76, v70
	v_mov_b32_e32 v77, v66
	v_mov_b32_e32 v70, v67
	v_mov_b32_e32 v66, v71
	v_mov_b32_e32 v78, v68
	v_mov_b32_e32 v79, v72
	v_mov_b32_e32 v80, v72
	v_mov_b32_e32 v81, v68
	v_mov_b32_e32 v72, v69
	v_mov_b32_e32 v68, v73
	v_pk_mul_f32 v[22:23], v[22:23], v[38:39]
	v_pk_mul_f32 v[10:11], v[10:11], v[40:41]
	v_pk_mul_f32 v[18:19], v[18:19], v[36:37]
	v_pk_mul_f32 v[12:13], v[12:13], v[34:35]
	v_pk_mul_f32 v[20:21], v[20:21], v[32:33]
	v_pk_mul_f32 v[30:31], v[56:57], v[30:31]
	v_pk_mul_f32 v[28:29], v[52:53], v[28:29]
	v_pk_mul_f32 v[26:27], v[58:59], v[26:27]
	v_pk_mul_f32 v[24:25], v[24:25], v[22:23]
	v_pk_mul_f32 v[22:23], v[42:43], v[22:23]
	v_pk_mul_f32 v[6:7], v[6:7], v[10:11]
	v_pk_mul_f32 v[2:3], v[2:3], v[10:11]
	v_pk_mul_f32 v[10:11], v[44:45], v[18:19]
	v_pk_mul_f32 v[18:19], v[46:47], v[18:19]
	v_pk_mul_f32 v[8:9], v[8:9], v[12:13]
	v_pk_mul_f32 v[4:5], v[4:5], v[12:13]
	v_pk_mul_f32 v[12:13], v[48:49], v[20:21]
	v_pk_mul_f32 v[20:21], v[76:77], v[20:21]
	v_pk_mul_f32 v[32:33], v[70:71], v[30:31]
	v_pk_mul_f32 v[30:31], v[66:67], v[30:31]
	v_pk_mul_f32 v[34:35], v[78:79], v[28:29]
	v_pk_mul_f32 v[28:29], v[80:81], v[28:29]
	v_pk_mul_f32 v[36:37], v[72:73], v[26:27]
	v_pk_mul_f32 v[26:27], v[68:69], v[26:27]
	v_sub_f32_e32 v24, v24, v25
	v_add_f32_e32 v22, v22, v23
	v_sub_f32_e32 v6, v6, v7
	v_add_f32_e32 v7, v2, v3
	v_sub_f32_e32 v3, v10, v11
	v_add_f32_e32 v10, v18, v19
	v_sub_f32_e32 v8, v8, v9
	v_add_f32_e32 v9, v4, v5
	v_sub_f32_e32 v4, v12, v13
	v_add_f32_e32 v11, v20, v21
	v_sub_f32_e32 v5, v32, v33
	v_add_f32_e32 v12, v30, v31
	v_sub_f32_e32 v13, v34, v35
	v_add_f32_e32 v18, v28, v29
	v_sub_f32_e32 v19, v36, v37
	v_add_f32_e32 v20, v26, v27
	v_cvt_pk_bf16_f32 v2, v24, v6
	v_cvt_pk_bf16_f32 v3, v3, v8
	v_cvt_pk_bf16_f32 v4, v4, v5
	v_cvt_pk_bf16_f32 v5, v13, v19
	v_cvt_pk_bf16_f32 v6, v22, v7
	v_cvt_pk_bf16_f32 v7, v10, v9
	v_cvt_pk_bf16_f32 v8, v11, v12
	v_cvt_pk_bf16_f32 v9, v18, v20
	global_load_dwordx4 v[10:13], v[14:15], off offset:384
	s_nop 0
	global_load_dwordx4 v[14:17], v[16:17], off offset:384
	s_nop 0
	global_load_dwordx4 v[18:21], v[50:51], off
	global_load_dwordx4 v[22:25], v[60:61], off
	global_load_dwordx4 v[26:29], v[74:75], off
	v_and_b32_e32 v30, 0xfffff0, v82
	v_lshlrev_b32_e32 v31, 1, v82
	v_lshrrev_b32_e32 v32, 1, v82
	v_and_b32_e32 v34, 3, v82
	v_add_u32_e32 v35, 32, v82
	v_and_or_b32 v30, v31, 8, v30
	v_and_or_b32 v31, v32, 4, v34
	v_and_b32_e32 v32, 0xfffff0, v35
	v_lshlrev_b32_e32 v34, 1, v35
	v_and_or_b32 v32, v34, 8, v32
	v_bfe_u32 v33, v83, 5, 2
	v_lshrrev_b32_e32 v30, 1, v30
	v_lshrrev_b32_e32 v32, 1, v32
	v_lshrrev_b32_e32 v34, 3, v84
	v_or_b32_e32 v30, v30, v33
	v_or_b32_e32 v32, v32, v33
	v_lshrrev_b32_e32 v33, 1, v87
	v_and_b32_e32 v36, 48, v112
	v_lshlrev_b32_e32 v31, 6, v31
	v_lshrrev_b32_e32 v35, 3, v85
	v_lshrrev_b32_e32 v37, 3, v86
	v_lshlrev_b32_e32 v30, 9, v30
	v_xor_b32_e32 v34, v34, v87
	v_mul_lo_u32 v33, v33, s62
	v_lshrrev_b32_e32 v38, 1, v88
	v_lshrrev_b32_e32 v39, 1, v89
	v_lshlrev_b32_e32 v32, 9, v32
	v_lshlrev_b32_e32 v34, 4, v34
	v_xor_b32_e32 v35, v35, v88
	v_xor_b32_e32 v37, v37, v89
	v_or3_b32 v30, v30, v31, v36
	v_lshl_add_u32 v33, v84, 5, v33
	v_mul_lo_u32 v38, v38, s62
	v_mul_lo_u32 v39, v39, s62
	v_lshlrev_b32_e32 v35, 4, v35
	v_lshlrev_b32_e32 v37, 4, v37
	v_or3_b32 v31, v32, v31, v36
	v_add_u32_e32 v181, 0, v30
	v_and_or_b32 v30, v34, 16, v33
	v_lshl_add_u32 v32, v85, 5, v38
	v_lshl_add_u32 v33, v86, 5, v39
	v_add_u32_e32 v182, 0, v31
	v_and_or_b32 v31, v35, 16, v32
	v_and_or_b32 v32, v37, 16, v33
	ds_write_b128 v177, v[2:5] offset:1024
	ds_write_b128 v177, v[6:9] offset:3072
	v_add_u32_e32 v183, 0, v30
	v_add_u32_e32 v192, 0, v31
	v_add_u32_e32 v193, 0, v32
	s_waitcnt vmcnt(0)
	s_waitcnt vmcnt(4)
	ds_write_b128 v181, v[10:13]
	s_waitcnt vmcnt(3)
	ds_write_b128 v182, v[14:17]
	s_waitcnt vmcnt(2)
	ds_write_b128 v183, v[18:21] offset:32768
	s_waitcnt vmcnt(1)
	ds_write_b128 v192, v[22:25] offset:32768
	s_waitcnt vmcnt(0)
	ds_write_b128 v193, v[26:29] offset:32768
	s_waitcnt lgkmcnt(0)
	s_barrier
	ds_read_b128 v[2:5], v113
	ds_read_b128 v[6:9], v113 offset:1024
	s_waitcnt lgkmcnt(1)
	v_mfma_f32_32x32x16_bf16 v[82:97], v[2:5], v[116:119], 0
	v_lshl_add_u64 v[46:47], s[6:7], 0, v[100:101]
	v_lshl_add_u64 v[48:49], s[6:7], 0, v[102:103]
	v_lshl_add_u64 v[40:41], s[8:9], 0, v[62:63]
	v_lshl_add_u64 v[42:43], s[8:9], 0, v[64:65]
	v_lshl_add_u64 v[44:45], s[8:9], 0, v[98:99]
	v_and_b32_e32 v112, 0xc0, v112
	v_and_or_b32 v112, v160, 24, v112
	s_waitcnt lgkmcnt(0)
	v_mfma_f32_32x32x16_bf16 v[66:81], v[6:9], v[116:119], 0
	ds_read_b128 v[2:5], v113 offset:2080
	ds_read_b128 v[6:9], v113 offset:3104
	v_readlane_b32 s8, v254, 60
	v_readlane_b32 s12, v255, 0
	v_readlane_b32 s13, v255, 1
	v_mov_b32_e32 v18, 0
	v_mov_b32_e32 v34, 0
	v_mov_b32_e32 v50, 0
	s_waitcnt lgkmcnt(1)
	v_mfma_f32_32x32x16_bf16 v[82:97], v[2:5], v[120:123], v[82:97]
	v_mov_b32_e32 v19, v180
	v_mov_b32_e32 v35, v180
	v_mov_b32_e32 v51, v180
	v_mov_b32_e32 v60, v180
	v_mov_b32_e32 v61, v180
	v_readlane_b32 s9, v254, 61
	v_readlane_b32 s10, v254, 62
	s_waitcnt lgkmcnt(0)
	v_mfma_f32_32x32x16_bf16 v[66:81], v[6:9], v[120:123], v[66:81]
	ds_read_b128 v[2:5], v113 offset:4160
	ds_read_b128 v[6:9], v113 offset:5184
	ds_read_b128 v[10:13], v113 offset:6240
	ds_read_b128 v[14:17], v113 offset:7264
	ds_read_b128 v[20:23], v113 offset:8320
	ds_read_b128 v[24:27], v113 offset:9344
	ds_read_b128 v[28:31], v113 offset:10400
	ds_read_b128 v[36:39], v113 offset:11424
	s_waitcnt lgkmcnt(7)
	v_mfma_f32_32x32x16_bf16 v[82:97], v[2:5], v[124:127], v[82:97]
	global_load_dwordx4 v[104:107], v[46:47], off
	v_mov_b32_e32 v2, 0
	v_mov_b32_e32 v3, v180
	v_mov_b32_e32 v4, v180
	v_mov_b32_e32 v5, v180
	v_readlane_b32 s11, v254, 63
	v_readlane_b32 s14, v255, 2
	s_waitcnt lgkmcnt(6)
	v_mfma_f32_32x32x16_bf16 v[66:81], v[6:9], v[124:127], v[66:81]
	v_mov_b32_e32 v6, v180
	v_mov_b32_e32 v7, v180
	v_mov_b32_e32 v8, v180
	v_mov_b32_e32 v9, v180
	v_readlane_b32 s15, v255, 3
	s_waitcnt lgkmcnt(5)
	v_mfma_f32_32x32x16_bf16 v[82:97], v[10:13], v[128:131], v[82:97]
	v_mov_b32_e32 v10, v180
	v_mov_b32_e32 v11, v180
	v_mov_b32_e32 v12, v180
	v_mov_b32_e32 v13, v180
	s_waitcnt lgkmcnt(4)
	v_mfma_f32_32x32x16_bf16 v[66:81], v[14:17], v[128:131], v[66:81]
	v_mov_b32_e32 v14, v180
	v_mov_b32_e32 v15, v180
	v_mov_b32_e32 v16, v180
	v_mov_b32_e32 v17, v180
	s_waitcnt lgkmcnt(3)
	v_mfma_f32_32x32x16_bf16 v[82:97], v[20:23], v[132:135], v[82:97]
	v_mov_b32_e32 v20, v180
	v_mov_b32_e32 v21, v180
	v_mov_b32_e32 v22, v180
	v_mov_b32_e32 v23, v180
	s_waitcnt lgkmcnt(2)
	v_mfma_f32_32x32x16_bf16 v[66:81], v[24:27], v[132:135], v[66:81]
	v_mov_b32_e32 v24, v180
	v_mov_b32_e32 v25, v180
	v_mov_b32_e32 v26, v180
	v_mov_b32_e32 v27, v180
	s_waitcnt lgkmcnt(1)
	v_mfma_f32_32x32x16_bf16 v[82:97], v[28:31], v[136:139], v[82:97]
	ds_read_b128 v[30:33], v113 offset:12480
	v_mov_b32_e32 v28, v180
	v_mov_b32_e32 v29, v180
	s_waitcnt lgkmcnt(1)
	v_mfma_f32_32x32x16_bf16 v[66:81], v[36:39], v[136:139], v[66:81]
	ds_read_b128 v[36:39], v113 offset:13504
	global_load_dwordx4 v[108:111], v[48:49], off
	global_load_dwordx4 v[164:167], v[40:41], off
	global_load_dwordx4 v[168:171], v[42:43], off
	global_load_dwordx4 v[194:197], v[44:45], off
	ds_read_b128 v[40:43], v113 offset:14560
	ds_read_b128 v[46:49], v113 offset:15584
	ds_read_b128 v[52:55], v113 offset:16640
	ds_read_b128 v[56:59], v177
	ds_read_b128 v[148:151], v113 offset:17664
	ds_read_b128 v[152:155], v177 offset:1024
	s_waitcnt lgkmcnt(7)
	v_mfma_f32_32x32x16_bf16 v[82:97], v[30:33], v[140:143], v[82:97]
	ds_read_b128 v[156:159], v113 offset:18720
	v_mov_b32_e32 v30, v180
	v_mov_b32_e32 v31, v180
	v_mov_b32_e32 v32, v180
	v_mov_b32_e32 v33, v180
	v_mov_b32_e32 v44, v180
	v_mov_b32_e32 v45, v180
	s_waitcnt lgkmcnt(7)
	v_mfma_f32_32x32x16_bf16 v[66:81], v[36:39], v[140:143], v[66:81]
	v_mov_b32_e32 v36, v180
	v_mov_b32_e32 v37, v180
	v_mov_b32_e32 v38, v180
	v_mov_b32_e32 v39, v180
	s_waitcnt lgkmcnt(6)
	v_mfma_f32_32x32x16_bf16 v[82:97], v[40:43], v[144:147], v[82:97]
	v_mov_b32_e32 v40, v180
	v_mov_b32_e32 v41, v180
	v_mov_b32_e32 v42, v180
	v_mov_b32_e32 v43, v180
	s_waitcnt lgkmcnt(5)
	v_mfma_f32_32x32x16_bf16 v[66:81], v[46:49], v[144:147], v[66:81]
	v_mov_b32_e32 v46, v180
	v_mov_b32_e32 v47, v180
	v_mov_b32_e32 v48, v180
	v_mov_b32_e32 v49, v180
	s_waitcnt lgkmcnt(3)
	v_mfma_f32_32x32x16_bf16 v[82:97], v[52:55], v[56:59], v[82:97]
	v_mov_b32_e32 v52, v180
	v_mov_b32_e32 v53, v180
	v_mov_b32_e32 v54, v180
	v_mov_b32_e32 v55, v180
	s_waitcnt lgkmcnt(2)
	v_mfma_f32_32x32x16_bf16 v[66:81], v[148:151], v[56:59], v[66:81]
	ds_read_b128 v[148:151], v113 offset:19744
	v_mov_b32_e32 v56, v180
	v_mov_b32_e32 v57, v180
	v_mov_b32_e32 v58, v180
	v_mov_b32_e32 v59, v180
	s_waitcnt lgkmcnt(1)
	v_mfma_f32_32x32x16_bf16 v[82:97], v[156:159], v[152:155], v[82:97]
	v_lshlrev_b32_e32 v156, 1, v175
	v_and_b32_e32 v161, 32, v156
	ds_read_b128 v[156:159], v113 offset:20800
	s_waitcnt lgkmcnt(1)
	v_mfma_f32_32x32x16_bf16 v[66:81], v[148:151], v[152:155], v[66:81]
	ds_read_b128 v[150:153], v177 offset:2048
	v_and_b32_e32 v148, 0x100, v160
	v_or3_b32 v112, v112, v161, v148
	v_add_u32_e32 v179, s1, v112
	s_addk_i32 s1, 0x4000
	ds_read_b128 v[198:201], v113 offset:21824
	ds_read_b128 v[202:205], v177 offset:3072
	v_add_u32_e32 v176, s1, v112
	s_add_u32 s1, s81, s82
	ds_read_b128 v[206:209], v113 offset:22880
	s_waitcnt lgkmcnt(3)
	v_mfma_f32_32x32x16_bf16 v[82:97], v[156:159], v[150:153], v[82:97]
	s_addc_u32 s3, s80, 0
	s_add_u32 s6, s12, s1
	s_addc_u32 s7, s13, s3
	v_lshl_add_u64 v[148:149], s[6:7], 0, v[98:99]
	v_lshl_add_u64 v[154:155], s[6:7], 0, v[100:101]
	v_lshl_add_u64 v[156:157], s[6:7], 0, v[102:103]
	s_waitcnt lgkmcnt(2)
	v_mfma_f32_32x32x16_bf16 v[66:81], v[198:201], v[150:153], v[66:81]
	v_lshl_add_u64 v[150:151], s[6:7], 0, v[64:65]
	v_lshl_add_u64 v[152:153], s[6:7], 0, v[62:63]
	ds_read_b128 v[62:65], v113 offset:23904
	s_waitcnt vmcnt(0)
	s_waitcnt vmcnt(4)
	ds_write_b128 v181, v[104:107] offset:16384
	s_waitcnt vmcnt(3)
	ds_write_b128 v182, v[108:111] offset:16384
	s_waitcnt vmcnt(2)
	ds_write_b128 v183, v[164:167] offset:57728
	s_waitcnt vmcnt(1)
	ds_write_b128 v192, v[168:171] offset:57728
	s_waitcnt vmcnt(0)
	ds_write_b128 v193, v[194:197] offset:57728
	s_waitcnt lgkmcnt(0)
	v_mfma_f32_32x32x16_bf16 v[82:97], v[206:209], v[202:205], v[82:97]
	s_barrier
	v_mfma_f32_32x32x16_bf16 v[66:81], v[62:65], v[202:205], v[66:81]
	s_nop 9
	v_exp_f32_e32 v197, v82
	v_exp_f32_e32 v199, v83
	v_exp_f32_e32 v195, v84
	v_exp_f32_e32 v198, v85
	v_exp_f32_e32 v194, v86
	v_exp_f32_e32 v196, v87
	v_exp_f32_e32 v170, v88
	v_exp_f32_e32 v171, v89
	v_exp_f32_e32 v167, v90
	v_exp_f32_e32 v169, v91
	v_exp_f32_e32 v166, v92
	v_exp_f32_e32 v168, v93
	v_exp_f32_e32 v158, v94
	v_exp_f32_e32 v165, v95
	v_exp_f32_e32 v159, v96
	v_exp_f32_e32 v164, v97
	v_mov_b32_e32 v62, v180
	v_mov_b32_e32 v63, v180
	v_mov_b32_e32 v64, v180
	v_mov_b32_e32 v65, v180
	v_readfirstlane_b32 s1, v0
	s_bitcmp1_b32 s1, 8
	s_cbranch_scc0 .Lprio_skip
	s_setprio 1
.Lprio_skip:
.LBB0_803:
	v_add_u32_e32 v200, 0, v178
	ds_read_b128 v[82:85], v200 offset:57728
	ds_read_b128 v[86:89], v200 offset:58752
	ds_read_b128 v[202:205], v200 offset:59808
	ds_read_b128 v[206:209], v200 offset:60832
	v_add_u32_e32 v160, 0x8000, v200
	v_exp_f32_e32 v161, v67
	s_waitcnt lgkmcnt(3)
	v_mfma_f32_32x32x16_bf16 v[98:113], v[82:85], v[116:119], 0
	v_exp_f32_e32 v201, v68
	v_exp_f32_e32 v70, v70
	v_exp_f32_e32 v71, v71
	v_exp_f32_e32 v72, v72
	v_exp_f32_e32 v73, v73
	v_exp_f32_e32 v78, v78
	v_exp_f32_e32 v79, v79
	s_waitcnt lgkmcnt(2)
	v_mfma_f32_32x32x16_bf16 v[82:97], v[86:89], v[116:119], 0
	v_exp_f32_e32 v80, v80
	v_exp_f32_e32 v81, v81
	s_waitcnt lgkmcnt(1)
	v_mfma_f32_32x32x16_bf16 v[98:113], v[202:205], v[120:123], v[98:113]
	s_waitcnt lgkmcnt(0)
	v_mfma_f32_32x32x16_bf16 v[82:97], v[206:209], v[120:123], v[82:97]
	ds_read_b128 v[202:205], v200 offset:61888
	ds_read_b128 v[206:209], v200 offset:62912
	s_waitcnt lgkmcnt(1)
	v_mfma_f32_32x32x16_bf16 v[98:113], v[202:205], v[124:127], v[98:113]
	s_waitcnt lgkmcnt(0)
	v_mfma_f32_32x32x16_bf16 v[82:97], v[206:209], v[124:127], v[82:97]
	ds_read_b128 v[202:205], v200 offset:63968
	ds_read_b128 v[206:209], v200 offset:64992
	s_waitcnt lgkmcnt(1)
	v_mfma_f32_32x32x16_bf16 v[98:113], v[202:205], v[128:131], v[98:113]
	s_waitcnt lgkmcnt(0)
	v_mfma_f32_32x32x16_bf16 v[82:97], v[206:209], v[128:131], v[82:97]
	ds_read_b128 v[202:205], v160 offset:33280
	ds_read_b128 v[206:209], v160 offset:34304
	s_waitcnt lgkmcnt(1)
	v_mfma_f32_32x32x16_bf16 v[98:113], v[202:205], v[132:135], v[98:113]
	s_waitcnt lgkmcnt(0)
	v_mfma_f32_32x32x16_bf16 v[82:97], v[206:209], v[132:135], v[82:97]
	ds_read_b128 v[202:205], v160 offset:35360
	ds_read_b128 v[206:209], v160 offset:36384
	s_waitcnt lgkmcnt(1)
	v_mfma_f32_32x32x16_bf16 v[98:113], v[202:205], v[136:139], v[98:113]
	s_waitcnt lgkmcnt(0)
	v_mfma_f32_32x32x16_bf16 v[82:97], v[206:209], v[136:139], v[82:97]
	ds_read_b128 v[202:205], v160 offset:37440
	ds_read_b128 v[206:209], v160 offset:38464
	s_waitcnt lgkmcnt(1)
	v_mfma_f32_32x32x16_bf16 v[98:113], v[202:205], v[140:143], v[98:113]
	s_waitcnt lgkmcnt(0)
	v_mfma_f32_32x32x16_bf16 v[82:97], v[206:209], v[140:143], v[82:97]
	ds_read_b128 v[202:205], v160 offset:39520
	ds_read_b128 v[206:209], v160 offset:40544
	s_waitcnt lgkmcnt(1)
	v_mfma_f32_32x32x16_bf16 v[98:113], v[202:205], v[144:147], v[98:113]
	s_waitcnt lgkmcnt(0)
	v_mfma_f32_32x32x16_bf16 v[82:97], v[206:209], v[144:147], v[82:97]
	ds_read_b128 v[202:205], v160 offset:41600
	ds_read_b128 v[206:209], v160 offset:42624
	ds_read_b128 v[210:213], v177
	s_waitcnt lgkmcnt(0)
	v_mfma_f32_32x32x16_bf16 v[98:113], v[202:205], v[210:213], v[98:113]
	v_mfma_f32_32x32x16_bf16 v[82:97], v[206:209], v[210:213], v[82:97]
	ds_read_b128 v[202:205], v160 offset:43680
	ds_read_b128 v[206:209], v160 offset:44704
	ds_read_b128 v[210:213], v177 offset:1024
	s_waitcnt lgkmcnt(0)
	v_mfma_f32_32x32x16_bf16 v[98:113], v[202:205], v[210:213], v[98:113]
	v_mfma_f32_32x32x16_bf16 v[82:97], v[206:209], v[210:213], v[82:97]
	ds_read_b128 v[202:205], v160 offset:45760
	ds_read_b128 v[206:209], v160 offset:46784
	ds_read_b128 v[210:213], v177 offset:2048
	s_waitcnt lgkmcnt(0)
	v_mfma_f32_32x32x16_bf16 v[98:113], v[202:205], v[210:213], v[98:113]
	v_mfma_f32_32x32x16_bf16 v[82:97], v[206:209], v[210:213], v[82:97]
	ds_read_b128 v[202:205], v160 offset:47840
	ds_read_b128 v[206:209], v160 offset:48864
	ds_read_b128 v[210:213], v177 offset:3072
	v_exp_f32_e32 v160, v66
	v_add_f32_e32 v66, 0, v197
	v_add_f32_e32 v66, v199, v66
	v_add_f32_e32 v66, v195, v66
	v_add_f32_e32 v66, v198, v66
	v_add_f32_e32 v66, v194, v66
	v_add_f32_e32 v66, v196, v66
	v_add_f32_e32 v66, v170, v66
	v_add_f32_e32 v66, v171, v66
	v_add_f32_e32 v66, v167, v66
	v_add_f32_e32 v66, v169, v66
	v_add_f32_e32 v66, v166, v66
	v_add_f32_e32 v66, v168, v66
	v_add_f32_e32 v66, v158, v66
	v_add_f32_e32 v66, v165, v66
	v_add_f32_e32 v66, v159, v66
	s_waitcnt lgkmcnt(0)
	v_mfma_f32_32x32x16_bf16 v[98:113], v[202:205], v[210:213], v[98:113]
	v_exp_f32_e32 v202, v69
	v_add_f32_e32 v66, v164, v66
	v_add_f32_e32 v66, v160, v66
	v_add_f32_e32 v66, v161, v66
	v_add_f32_e32 v66, v201, v66
	v_add_f32_e32 v66, v202, v66
	v_exp_f32_e32 v203, v74
	v_add_f32_e32 v66, v70, v66
	v_exp_f32_e32 v204, v75
	v_add_f32_e32 v66, v71, v66
	v_exp_f32_e32 v205, v76
	v_add_f32_e32 v66, v72, v66
	v_mfma_f32_32x32x16_bf16 v[82:97], v[206:209], v[210:213], v[82:97]
	v_exp_f32_e32 v206, v77
	v_add_f32_e32 v66, v73, v66
	v_add_f32_e32 v66, v203, v66
	v_add_f32_e32 v66, v204, v66
	v_add_f32_e32 v66, v205, v66
	v_add_f32_e32 v66, v206, v66
	v_add_f32_e32 v66, v78, v66
	v_add_f32_e32 v66, v79, v66
	v_add_f32_e32 v66, v80, v66
	v_add_f32_e32 v66, v81, v66
	v_mov_b32_e32 v67, v66
	s_nop 1
	v_permlane32_swap_b32_e32 v66, v67
	v_add_f32_e32 v66, v66, v67
	v_add_f32_e32 v180, v180, v66
	v_cvt_pk_bf16_f32 v66, v197, v199
	v_cvt_pk_bf16_f32 v67, v195, v198
	v_cvt_pk_bf16_f32 v68, v194, v196
	v_cvt_pk_bf16_f32 v69, v170, v171
	v_cvt_pk_bf16_f32 v74, v167, v169
	v_cvt_pk_bf16_f32 v75, v166, v168
	v_cvt_pk_bf16_f32 v76, v158, v165
	v_cvt_pk_bf16_f32 v77, v159, v164
	v_cvt_pk_bf16_f32 v194, v160, v161
	v_cvt_pk_bf16_f32 v195, v201, v202
	v_cvt_pk_bf16_f32 v196, v70, v71
	v_cvt_pk_bf16_f32 v197, v72, v73
	s_nop 0
	v_permlane32_swap_b32_e32 v66, v68
	v_permlane32_swap_b32_e32 v67, v69
	v_permlane32_swap_b32_e32 v74, v76
	v_permlane32_swap_b32_e32 v75, v77
	v_permlane32_swap_b32_e32 v194, v196
	v_permlane32_swap_b32_e32 v195, v197
	v_cvt_pk_bf16_f32 v202, v203, v204
	v_cvt_pk_bf16_f32 v203, v205, v206
	v_cvt_pk_bf16_f32 v204, v78, v79
	v_cvt_pk_bf16_f32 v205, v80, v81
	s_nop 0
	v_permlane32_swap_b32_e32 v202, v204
	v_permlane32_swap_b32_e32 v203, v205
	v_lshl_add_u64 v[158:159], v[154:155], 0, s[42:43]
	v_add_co_u32_e32 v70, vcc, s33, v158
	v_lshl_add_u64 v[164:165], v[156:157], 0, s[42:43]
	s_nop 0
	v_addc_co_u32_e32 v71, vcc, 0, v159, vcc
	v_add_co_u32_e32 v78, vcc, s33, v164
	v_lshl_add_u64 v[166:167], v[152:153], 0, s[42:43]
	s_nop 0
	v_addc_co_u32_e32 v79, vcc, 0, v165, vcc
	v_add_co_u32_e32 v168, vcc, s33, v166
	global_load_dwordx4 v[70:73], v[70:71], off offset:384
	s_nop 0
	v_addc_co_u32_e32 v169, vcc, 0, v167, vcc
	global_load_dwordx4 v[206:209], v[168:169], off
	v_lshl_add_u64 v[168:169], v[150:151], 0, s[42:43]
	v_add_co_u32_e32 v170, vcc, s33, v168
	global_load_dwordx4 v[78:81], v[78:79], off offset:384
	s_nop 0
	v_addc_co_u32_e32 v171, vcc, 0, v169, vcc
	global_load_dwordx4 v[210:213], v[170:171], off
	v_lshl_add_u64 v[170:171], v[148:149], 0, s[42:43]
	v_add_co_u32_e32 v198, vcc, s33, v170
	s_nop 1
	v_addc_co_u32_e32 v199, vcc, 0, v171, vcc
	global_load_dwordx4 v[214:217], v[198:199], off
	ds_read_b64_tr_b16 v[218:219], v179 offset:0
	ds_read_b64_tr_b16 v[220:221], v179 offset:0x800
	ds_read_b64_tr_b16 v[222:223], v179 offset:0x1000
	ds_read_b64_tr_b16 v[224:225], v179 offset:0x1800
	ds_read_b64_tr_b16 v[240:241], v179 offset:0x2000
	ds_read_b64_tr_b16 v[242:243], v179 offset:0x2800
	ds_read_b64_tr_b16 v[244:245], v179 offset:0x3000
	ds_read_b64_tr_b16 v[246:247], v179 offset:0x3800
	s_waitcnt lgkmcnt(0)
	s_nop 0
	v_mfma_f32_32x32x16_bf16 v[2:17], v[66:69], v[218:221], v[2:17]
	ds_read_b64_tr_b16 v[218:219], v179 offset:0x200
	ds_read_b64_tr_b16 v[220:221], v179 offset:0xa00
	v_mfma_f32_32x32x16_bf16 v[2:17], v[74:77], v[222:225], v[2:17]
	ds_read_b64_tr_b16 v[222:223], v179 offset:0x1200
	ds_read_b64_tr_b16 v[224:225], v179 offset:0x1a00
	v_mfma_f32_32x32x16_bf16 v[2:17], v[194:197], v[240:243], v[2:17]
	ds_read_b64_tr_b16 v[240:241], v179 offset:0x2200
	ds_read_b64_tr_b16 v[242:243], v179 offset:0x2a00
	v_mfma_f32_32x32x16_bf16 v[2:17], v[202:205], v[244:247], v[2:17]
	ds_read_b64_tr_b16 v[244:245], v179 offset:0x3200
	ds_read_b64_tr_b16 v[246:247], v179 offset:0x3a00
	s_waitcnt lgkmcnt(0)
	v_mfma_f32_32x32x16_bf16 v[18:33], v[66:69], v[218:221], v[18:33]
	ds_read_b64_tr_b16 v[218:219], v179 offset:0x400
	ds_read_b64_tr_b16 v[220:221], v179 offset:0xc00
	v_mfma_f32_32x32x16_bf16 v[18:33], v[74:77], v[222:225], v[18:33]
	ds_read_b64_tr_b16 v[222:223], v179 offset:0x1400
	ds_read_b64_tr_b16 v[224:225], v179 offset:0x1c00
	v_mfma_f32_32x32x16_bf16 v[18:33], v[194:197], v[240:243], v[18:33]
	ds_read_b64_tr_b16 v[240:241], v179 offset:0x2400
	ds_read_b64_tr_b16 v[242:243], v179 offset:0x2c00
	v_mfma_f32_32x32x16_bf16 v[18:33], v[202:205], v[244:247], v[18:33]
	ds_read_b64_tr_b16 v[244:245], v179 offset:0x3400
	ds_read_b64_tr_b16 v[246:247], v179 offset:0x3c00
	s_waitcnt lgkmcnt(0)
	v_mfma_f32_32x32x16_bf16 v[34:49], v[66:69], v[218:221], v[34:49]
	ds_read_b64_tr_b16 v[218:219], v179 offset:0x600
	ds_read_b64_tr_b16 v[220:221], v179 offset:0xe00
	v_mfma_f32_32x32x16_bf16 v[34:49], v[74:77], v[222:225], v[34:49]
	ds_read_b64_tr_b16 v[222:223], v179 offset:0x1600
	ds_read_b64_tr_b16 v[224:225], v179 offset:0x1e00
	v_mfma_f32_32x32x16_bf16 v[34:49], v[194:197], v[240:243], v[34:49]
	ds_read_b64_tr_b16 v[240:241], v179 offset:0x2600
	ds_read_b64_tr_b16 v[242:243], v179 offset:0x2e00
	v_mfma_f32_32x32x16_bf16 v[34:49], v[202:205], v[244:247], v[34:49]
	ds_read_b64_tr_b16 v[244:245], v179 offset:0x3600
	ds_read_b64_tr_b16 v[246:247], v179 offset:0x3e00
	s_waitcnt lgkmcnt(0)
	v_mfma_f32_32x32x16_bf16 v[50:65], v[66:69], v[218:221], v[50:65]
	s_barrier
	s_waitcnt vmcnt(0)
	v_exp_f32_e32 v160, v98
	v_exp_f32_e32 v161, v99
	v_exp_f32_e32 v218, v100
	v_mfma_f32_32x32x16_bf16 v[50:65], v[74:77], v[222:225], v[50:65]
	v_exp_f32_e32 v219, v101
	v_exp_f32_e32 v220, v102
	v_exp_f32_e32 v221, v103
	v_exp_f32_e32 v222, v104
	v_exp_f32_e32 v223, v105
	v_exp_f32_e32 v224, v106
	v_exp_f32_e32 v225, v107
	v_mfma_f32_32x32x16_bf16 v[50:65], v[194:197], v[240:243], v[50:65]
	v_exp_f32_e32 v230, v108
	v_exp_f32_e32 v231, v109
	v_exp_f32_e32 v232, v110
	v_exp_f32_e32 v233, v111
	v_exp_f32_e32 v236, v112
	v_exp_f32_e32 v237, v113
	s_waitcnt vmcnt(4)
	ds_write_b128 v181, v[70:73]
	s_waitcnt vmcnt(2)
	ds_write_b128 v182, v[78:81]
	ds_write_b128 v183, v[206:209] offset:32768
	s_waitcnt vmcnt(1)
	ds_write_b128 v192, v[210:213] offset:32768
	s_waitcnt vmcnt(0)
	ds_write_b128 v193, v[214:217] offset:32768
	v_mfma_f32_32x32x16_bf16 v[50:65], v[202:205], v[244:247], v[50:65]
	s_waitcnt lgkmcnt(0)
	s_barrier
	ds_read_b128 v[66:69], v200 offset:32768
	ds_read_b128 v[70:73], v200 offset:33792
	ds_read_b128 v[194:197], v200 offset:34848
	ds_read_b128 v[202:205], v200 offset:35872
	v_exp_f32_e32 v86, v86
	v_exp_f32_e32 v87, v87
	s_waitcnt lgkmcnt(3)
	v_mfma_f32_32x32x16_bf16 v[98:113], v[66:69], v[116:119], 0
	v_exp_f32_e32 v88, v88
	v_exp_f32_e32 v89, v89
	s_waitcnt lgkmcnt(2)
	v_mfma_f32_32x32x16_bf16 v[66:81], v[70:73], v[116:119], 0
	s_waitcnt lgkmcnt(1)
	v_mfma_f32_32x32x16_bf16 v[98:113], v[194:197], v[120:123], v[98:113]
	s_waitcnt lgkmcnt(0)
	v_mfma_f32_32x32x16_bf16 v[66:81], v[202:205], v[120:123], v[66:81]
	ds_read_b128 v[194:197], v200 offset:36928
	ds_read_b128 v[202:205], v200 offset:37952
	s_waitcnt lgkmcnt(1)
	v_mfma_f32_32x32x16_bf16 v[98:113], v[194:197], v[124:127], v[98:113]
	s_waitcnt lgkmcnt(0)
	v_mfma_f32_32x32x16_bf16 v[66:81], v[202:205], v[124:127], v[66:81]
	ds_read_b128 v[194:197], v200 offset:39008
	ds_read_b128 v[202:205], v200 offset:40032
	s_waitcnt lgkmcnt(1)
	v_mfma_f32_32x32x16_bf16 v[98:113], v[194:197], v[128:131], v[98:113]
	s_waitcnt lgkmcnt(0)
	v_mfma_f32_32x32x16_bf16 v[66:81], v[202:205], v[128:131], v[66:81]
	ds_read_b128 v[194:197], v200 offset:41088
	ds_read_b128 v[202:205], v200 offset:42112
	s_waitcnt lgkmcnt(1)
	v_mfma_f32_32x32x16_bf16 v[98:113], v[194:197], v[132:135], v[98:113]
	s_waitcnt lgkmcnt(0)
	v_mfma_f32_32x32x16_bf16 v[66:81], v[202:205], v[132:135], v[66:81]
	ds_read_b128 v[194:197], v200 offset:43168
	ds_read_b128 v[202:205], v200 offset:44192
	s_waitcnt lgkmcnt(1)
	v_mfma_f32_32x32x16_bf16 v[98:113], v[194:197], v[136:139], v[98:113]
	s_waitcnt lgkmcnt(0)
	v_mfma_f32_32x32x16_bf16 v[66:81], v[202:205], v[136:139], v[66:81]
	ds_read_b128 v[194:197], v200 offset:45248
	ds_read_b128 v[202:205], v200 offset:46272
	s_waitcnt lgkmcnt(1)
	v_mfma_f32_32x32x16_bf16 v[98:113], v[194:197], v[140:143], v[98:113]
	s_waitcnt lgkmcnt(0)
	v_mfma_f32_32x32x16_bf16 v[66:81], v[202:205], v[140:143], v[66:81]
	ds_read_b128 v[194:197], v200 offset:47328
	ds_read_b128 v[202:205], v200 offset:48352
	s_waitcnt lgkmcnt(1)
	v_mfma_f32_32x32x16_bf16 v[98:113], v[194:197], v[144:147], v[98:113]
	s_waitcnt lgkmcnt(0)
	v_mfma_f32_32x32x16_bf16 v[66:81], v[202:205], v[144:147], v[66:81]
	ds_read_b128 v[194:197], v200 offset:49408
	ds_read_b128 v[202:205], v200 offset:50432
	ds_read_b128 v[206:209], v177
	s_waitcnt lgkmcnt(0)
	v_mfma_f32_32x32x16_bf16 v[98:113], v[194:197], v[206:209], v[98:113]
	v_mfma_f32_32x32x16_bf16 v[66:81], v[202:205], v[206:209], v[66:81]
	ds_read_b128 v[194:197], v200 offset:51488
	ds_read_b128 v[202:205], v200 offset:52512
	ds_read_b128 v[206:209], v177 offset:1024
	s_waitcnt lgkmcnt(0)
	v_mfma_f32_32x32x16_bf16 v[98:113], v[194:197], v[206:209], v[98:113]
	v_mfma_f32_32x32x16_bf16 v[66:81], v[202:205], v[206:209], v[66:81]
	ds_read_b128 v[194:197], v200 offset:53568
	ds_read_b128 v[202:205], v200 offset:54592
	ds_read_b128 v[206:209], v177 offset:2048
	s_waitcnt lgkmcnt(0)
	v_mfma_f32_32x32x16_bf16 v[98:113], v[194:197], v[206:209], v[98:113]
	v_mfma_f32_32x32x16_bf16 v[66:81], v[202:205], v[206:209], v[66:81]
	ds_read_b128 v[194:197], v200 offset:55648
	ds_read_b128 v[198:201], v200 offset:56672
	ds_read_b128 v[202:205], v177 offset:3072
	s_waitcnt lgkmcnt(0)
	v_mfma_f32_32x32x16_bf16 v[98:113], v[194:197], v[202:205], v[98:113]
	v_exp_f32_e32 v194, v82
	v_add_f32_e32 v82, 0, v160
	v_add_f32_e32 v82, v161, v82
	v_add_f32_e32 v82, v218, v82
	v_add_f32_e32 v82, v219, v82
	v_add_f32_e32 v82, v220, v82
	v_add_f32_e32 v82, v221, v82
	v_add_f32_e32 v82, v222, v82
	v_add_f32_e32 v82, v223, v82
	v_add_f32_e32 v82, v224, v82
	v_add_f32_e32 v82, v225, v82
	v_add_f32_e32 v82, v230, v82
	v_add_f32_e32 v82, v231, v82
	v_add_f32_e32 v82, v232, v82
	v_exp_f32_e32 v195, v83
	v_add_f32_e32 v82, v233, v82
	v_exp_f32_e32 v196, v84
	v_add_f32_e32 v82, v236, v82
	v_exp_f32_e32 v197, v85
	v_add_f32_e32 v82, v237, v82
	v_add_f32_e32 v82, v194, v82
	v_add_f32_e32 v82, v195, v82
	v_add_f32_e32 v82, v196, v82
	v_add_f32_e32 v82, v197, v82
	v_mfma_f32_32x32x16_bf16 v[66:81], v[198:201], v[202:205], v[66:81]
	v_exp_f32_e32 v198, v90
	v_add_f32_e32 v82, v86, v82
	v_exp_f32_e32 v199, v91
	v_add_f32_e32 v82, v87, v82
	v_exp_f32_e32 v200, v92
	v_add_f32_e32 v82, v88, v82
	v_exp_f32_e32 v201, v93
	v_add_f32_e32 v82, v89, v82
	v_exp_f32_e32 v202, v94
	v_add_f32_e32 v82, v198, v82
	v_exp_f32_e32 v203, v95
	v_add_f32_e32 v82, v199, v82
	v_exp_f32_e32 v204, v96
	v_add_f32_e32 v82, v200, v82
	v_exp_f32_e32 v205, v97
	v_add_f32_e32 v82, v201, v82
	v_add_f32_e32 v82, v202, v82
	v_add_f32_e32 v82, v203, v82
	v_add_f32_e32 v82, v204, v82
	v_add_f32_e32 v82, v205, v82
	v_mov_b32_e32 v83, v82
	s_nop 1
	v_permlane32_swap_b32_e32 v82, v83
	v_add_f32_e32 v82, v82, v83
	v_add_f32_e32 v180, v180, v82
	v_cvt_pk_bf16_f32 v82, v160, v161
	v_cvt_pk_bf16_f32 v83, v218, v219
	v_cvt_pk_bf16_f32 v84, v220, v221
	v_cvt_pk_bf16_f32 v85, v222, v223
	v_cvt_pk_bf16_f32 v90, v224, v225
	v_cvt_pk_bf16_f32 v91, v230, v231
	v_cvt_pk_bf16_f32 v92, v232, v233
	v_cvt_pk_bf16_f32 v93, v236, v237
	v_cvt_pk_bf16_f32 v94, v194, v195
	v_cvt_pk_bf16_f32 v95, v196, v197
	v_cvt_pk_bf16_f32 v96, v86, v87
	v_cvt_pk_bf16_f32 v97, v88, v89
	v_cvt_pk_bf16_f32 v194, v198, v199
	v_cvt_pk_bf16_f32 v195, v200, v201
	v_cvt_pk_bf16_f32 v196, v202, v203
	v_cvt_pk_bf16_f32 v197, v204, v205
	s_nop 0
	v_permlane32_swap_b32_e32 v82, v84
	v_permlane32_swap_b32_e32 v194, v196
	v_permlane32_swap_b32_e32 v195, v197
	v_permlane32_swap_b32_e32 v83, v85
	v_permlane32_swap_b32_e32 v90, v92
	v_permlane32_swap_b32_e32 v91, v93
	v_permlane32_swap_b32_e32 v94, v96
	v_permlane32_swap_b32_e32 v95, v97
	v_add_co_u32_e32 v86, vcc, s60, v158
	s_nop 1
	v_addc_co_u32_e32 v87, vcc, 0, v159, vcc
	v_add_co_u32_e32 v158, vcc, s60, v164
	global_load_dwordx4 v[86:89], v[86:87], off offset:384
	s_nop 0
	v_addc_co_u32_e32 v159, vcc, 0, v165, vcc
	global_load_dwordx4 v[200:203], v[158:159], off offset:384
	v_add_co_u32_e32 v158, vcc, s60, v166
	s_nop 1
	v_addc_co_u32_e32 v159, vcc, 0, v167, vcc
	global_load_dwordx4 v[204:207], v[158:159], off
	v_add_co_u32_e32 v158, vcc, s60, v168
	s_nop 1
	v_addc_co_u32_e32 v159, vcc, 0, v169, vcc
	global_load_dwordx4 v[208:211], v[158:159], off
	v_add_co_u32_e32 v158, vcc, s60, v170
	s_nop 1
	v_addc_co_u32_e32 v159, vcc, 0, v171, vcc
	global_load_dwordx4 v[212:215], v[158:159], off
	ds_read_b64_tr_b16 v[164:165], v176 offset:0
	ds_read_b64_tr_b16 v[166:167], v176 offset:0x800
	ds_read_b64_tr_b16 v[168:169], v176 offset:0x1000
	ds_read_b64_tr_b16 v[170:171], v176 offset:0x1800
	ds_read_b64_tr_b16 v[216:217], v176 offset:0x2000
	ds_read_b64_tr_b16 v[218:219], v176 offset:0x2800
	ds_read_b64_tr_b16 v[220:221], v176 offset:0x3000
	ds_read_b64_tr_b16 v[222:223], v176 offset:0x3800
	s_waitcnt lgkmcnt(0)
	s_nop 0
	v_mfma_f32_32x32x16_bf16 v[2:17], v[82:85], v[164:167], v[2:17]
	ds_read_b64_tr_b16 v[164:165], v176 offset:0x200
	ds_read_b64_tr_b16 v[166:167], v176 offset:0xa00
	v_mfma_f32_32x32x16_bf16 v[2:17], v[90:93], v[168:171], v[2:17]
	ds_read_b64_tr_b16 v[168:169], v176 offset:0x1200
	ds_read_b64_tr_b16 v[170:171], v176 offset:0x1a00
	v_mfma_f32_32x32x16_bf16 v[2:17], v[94:97], v[216:219], v[2:17]
	ds_read_b64_tr_b16 v[216:217], v176 offset:0x2200
	ds_read_b64_tr_b16 v[218:219], v176 offset:0x2a00
	v_mfma_f32_32x32x16_bf16 v[2:17], v[194:197], v[220:223], v[2:17]
	ds_read_b64_tr_b16 v[220:221], v176 offset:0x3200
	ds_read_b64_tr_b16 v[222:223], v176 offset:0x3a00
	s_waitcnt lgkmcnt(0)
	v_mfma_f32_32x32x16_bf16 v[18:33], v[82:85], v[164:167], v[18:33]
	ds_read_b64_tr_b16 v[164:165], v176 offset:0x400
	ds_read_b64_tr_b16 v[166:167], v176 offset:0xc00
	v_mfma_f32_32x32x16_bf16 v[18:33], v[90:93], v[168:171], v[18:33]
	ds_read_b64_tr_b16 v[168:169], v176 offset:0x1400
	ds_read_b64_tr_b16 v[170:171], v176 offset:0x1c00
	v_mfma_f32_32x32x16_bf16 v[18:33], v[94:97], v[216:219], v[18:33]
	ds_read_b64_tr_b16 v[216:217], v176 offset:0x2400
	ds_read_b64_tr_b16 v[218:219], v176 offset:0x2c00
	v_mfma_f32_32x32x16_bf16 v[18:33], v[194:197], v[220:223], v[18:33]
	ds_read_b64_tr_b16 v[220:221], v176 offset:0x3400
	ds_read_b64_tr_b16 v[222:223], v176 offset:0x3c00
	s_waitcnt lgkmcnt(0)
	v_mfma_f32_32x32x16_bf16 v[34:49], v[82:85], v[164:167], v[34:49]
	ds_read_b64_tr_b16 v[164:165], v176 offset:0x600
	ds_read_b64_tr_b16 v[166:167], v176 offset:0xe00
	v_mfma_f32_32x32x16_bf16 v[34:49], v[90:93], v[168:171], v[34:49]
	ds_read_b64_tr_b16 v[168:169], v176 offset:0x1600
	ds_read_b64_tr_b16 v[170:171], v176 offset:0x1e00
	v_mfma_f32_32x32x16_bf16 v[34:49], v[94:97], v[216:219], v[34:49]
	ds_read_b64_tr_b16 v[216:217], v176 offset:0x2600
	ds_read_b64_tr_b16 v[218:219], v176 offset:0x2e00
	v_mfma_f32_32x32x16_bf16 v[34:49], v[194:197], v[220:223], v[34:49]
	ds_read_b64_tr_b16 v[220:221], v176 offset:0x3600
	ds_read_b64_tr_b16 v[222:223], v176 offset:0x3e00
	s_waitcnt lgkmcnt(0)
	v_mfma_f32_32x32x16_bf16 v[50:65], v[82:85], v[164:167], v[50:65]
	v_exp_f32_e32 v199, v99
	v_exp_f32_e32 v198, v101
	v_exp_f32_e32 v167, v106
	v_exp_f32_e32 v166, v108
	v_exp_f32_e32 v158, v110
	v_exp_f32_e32 v165, v111
	v_exp_f32_e32 v159, v112
	v_mfma_f32_32x32x16_bf16 v[50:65], v[90:93], v[168:171], v[50:65]
	v_exp_f32_e32 v170, v104
	v_exp_f32_e32 v171, v105
	v_exp_f32_e32 v169, v107
	v_exp_f32_e32 v168, v109
	v_exp_f32_e32 v164, v113
	s_barrier
	v_mfma_f32_32x32x16_bf16 v[50:65], v[94:97], v[216:219], v[50:65]
	s_waitcnt vmcnt(0)
	s_add_i32 s0, s0, 2
	v_lshl_add_u64 v[148:149], v[148:149], 0, s[96:97]
	v_lshl_add_u64 v[150:151], v[150:151], 0, s[96:97]
	v_lshl_add_u64 v[152:153], v[152:153], 0, s[96:97]
	v_lshl_add_u64 v[156:157], v[156:157], 0, s[96:97]
	v_mfma_f32_32x32x16_bf16 v[50:65], v[194:197], v[220:223], v[50:65]
	v_exp_f32_e32 v197, v98
	v_exp_f32_e32 v195, v100
	v_exp_f32_e32 v194, v102
	v_exp_f32_e32 v196, v103
	v_lshl_add_u64 v[154:155], v[154:155], 0, s[96:97]
	s_cmp_gt_u32 s0, 28
	s_waitcnt vmcnt(4)
	ds_write_b128 v181, v[86:89] offset:16384
	s_waitcnt vmcnt(3)
	ds_write_b128 v182, v[200:203] offset:16384
	s_waitcnt vmcnt(2)
	ds_write_b128 v183, v[204:207] offset:57728
	s_waitcnt vmcnt(1)
	ds_write_b128 v192, v[208:211] offset:57728
	s_waitcnt vmcnt(0)
	ds_write_b128 v193, v[212:215] offset:57728
	s_waitcnt lgkmcnt(0)
	s_barrier
	s_cbranch_scc0 .LBB0_803
	s_setprio 0
	v_and_b32_e32 v82, 0x3fffffc0, v175
	s_add_i32 s0, 0, 0x14300
	v_lshl_add_u32 v148, v82, 2, s0
	v_add_u32_e32 v149, s58, v178
	ds_read_b128 v[82:85], v149 offset:24960
	ds_read_b128 v[86:89], v149 offset:25984
	v_exp_f32_e32 v71, v71
	v_exp_f32_e32 v73, v73
	s_waitcnt lgkmcnt(1)
	v_mfma_f32_32x32x16_bf16 v[98:113], v[82:85], v[116:119], 0
	s_waitcnt lgkmcnt(0)
	v_mfma_f32_32x32x16_bf16 v[82:97], v[86:89], v[116:119], 0
	ds_read_b128 v[116:119], v149 offset:27040
	ds_read_b128 v[150:153], v149 offset:28064
	s_waitcnt lgkmcnt(1)
	v_mfma_f32_32x32x16_bf16 v[98:113], v[116:119], v[120:123], v[98:113]
	s_waitcnt lgkmcnt(0)
	v_mfma_f32_32x32x16_bf16 v[82:97], v[150:153], v[120:123], v[82:97]
	ds_read_b128 v[116:119], v149 offset:29120
	ds_read_b128 v[120:123], v149 offset:30144
	s_waitcnt lgkmcnt(1)
	v_mfma_f32_32x32x16_bf16 v[98:113], v[116:119], v[124:127], v[98:113]
	s_waitcnt lgkmcnt(0)
	v_mfma_f32_32x32x16_bf16 v[82:97], v[120:123], v[124:127], v[82:97]
	ds_read_b128 v[116:119], v149 offset:31200
	ds_read_b128 v[120:123], v149 offset:32224
	s_waitcnt lgkmcnt(1)
	v_mfma_f32_32x32x16_bf16 v[98:113], v[116:119], v[128:131], v[98:113]
	s_waitcnt lgkmcnt(0)
	v_mfma_f32_32x32x16_bf16 v[82:97], v[120:123], v[128:131], v[82:97]
	ds_read_b128 v[116:119], v149 offset:33280
	ds_read_b128 v[120:123], v149 offset:34304
	v_exp_f32_e32 v128, v80
	v_exp_f32_e32 v129, v81
	s_waitcnt lgkmcnt(1)
	v_mfma_f32_32x32x16_bf16 v[98:113], v[116:119], v[132:135], v[98:113]
	s_waitcnt lgkmcnt(0)
	v_mfma_f32_32x32x16_bf16 v[82:97], v[120:123], v[132:135], v[82:97]
	ds_read_b128 v[116:119], v149 offset:35360
	ds_read_b128 v[120:123], v149 offset:36384
	s_waitcnt lgkmcnt(1)
	v_mfma_f32_32x32x16_bf16 v[98:113], v[116:119], v[136:139], v[98:113]
	s_waitcnt lgkmcnt(0)
	v_mfma_f32_32x32x16_bf16 v[82:97], v[120:123], v[136:139], v[82:97]
	ds_read_b128 v[116:119], v149 offset:37440
	ds_read_b128 v[120:123], v149 offset:38464
	s_waitcnt lgkmcnt(1)
	v_mfma_f32_32x32x16_bf16 v[98:113], v[116:119], v[140:143], v[98:113]
	s_waitcnt lgkmcnt(0)
	v_mfma_f32_32x32x16_bf16 v[82:97], v[120:123], v[140:143], v[82:97]
	ds_read_b128 v[116:119], v149 offset:39520
	ds_read_b128 v[120:123], v149 offset:40544
	s_waitcnt lgkmcnt(1)
	v_mfma_f32_32x32x16_bf16 v[98:113], v[116:119], v[144:147], v[98:113]
	s_waitcnt lgkmcnt(0)
	v_mfma_f32_32x32x16_bf16 v[82:97], v[120:123], v[144:147], v[82:97]
	ds_read_b128 v[116:119], v149 offset:41600
	ds_read_b128 v[120:123], v149 offset:42624
	ds_read_b128 v[124:127], v177
	s_waitcnt lgkmcnt(0)
	v_mfma_f32_32x32x16_bf16 v[98:113], v[116:119], v[124:127], v[98:113]
	v_mfma_f32_32x32x16_bf16 v[82:97], v[120:123], v[124:127], v[82:97]
	ds_read_b128 v[116:119], v149 offset:43680
	ds_read_b128 v[120:123], v149 offset:44704
	ds_read_b128 v[124:127], v177 offset:1024
	s_waitcnt lgkmcnt(0)
	v_mfma_f32_32x32x16_bf16 v[98:113], v[116:119], v[124:127], v[98:113]
	v_mfma_f32_32x32x16_bf16 v[82:97], v[120:123], v[124:127], v[82:97]
	ds_read_b128 v[116:119], v149 offset:45760
	ds_read_b128 v[120:123], v149 offset:46784
	ds_read_b128 v[124:127], v177 offset:2048
	s_waitcnt lgkmcnt(0)
	v_mfma_f32_32x32x16_bf16 v[98:113], v[116:119], v[124:127], v[98:113]
	v_mfma_f32_32x32x16_bf16 v[82:97], v[120:123], v[124:127], v[82:97]
	ds_read_b128 v[116:119], v149 offset:47840
	ds_read_b128 v[120:123], v149 offset:48864
	ds_read_b128 v[124:127], v177 offset:3072
	s_waitcnt lgkmcnt(0)
	v_mfma_f32_32x32x16_bf16 v[98:113], v[116:119], v[124:127], v[98:113]
	v_exp_f32_e32 v116, v66
	v_add_f32_e32 v66, 0, v197
	v_add_f32_e32 v66, v199, v66
	v_add_f32_e32 v66, v195, v66
	v_add_f32_e32 v66, v198, v66
	v_add_f32_e32 v66, v194, v66
	v_add_f32_e32 v66, v196, v66
	v_add_f32_e32 v66, v170, v66
	v_add_f32_e32 v66, v171, v66
	v_add_f32_e32 v66, v167, v66
	v_add_f32_e32 v66, v169, v66
	v_add_f32_e32 v66, v166, v66
	v_add_f32_e32 v66, v168, v66
	v_add_f32_e32 v66, v158, v66
	v_exp_f32_e32 v117, v67
	v_add_f32_e32 v66, v165, v66
	v_exp_f32_e32 v118, v68
	v_add_f32_e32 v66, v159, v66
	v_exp_f32_e32 v119, v69
	v_add_f32_e32 v66, v164, v66
	v_mfma_f32_32x32x16_bf16 v[82:97], v[120:123], v[124:127], v[82:97]
	v_exp_f32_e32 v120, v70
	v_add_f32_e32 v66, v116, v66
	v_add_f32_e32 v66, v117, v66
	v_exp_f32_e32 v121, v72
	v_add_f32_e32 v66, v118, v66
	v_add_f32_e32 v66, v119, v66
	v_exp_f32_e32 v122, v74
	v_add_f32_e32 v66, v120, v66
	v_exp_f32_e32 v123, v75
	v_add_f32_e32 v66, v71, v66
	v_exp_f32_e32 v124, v76
	v_add_f32_e32 v66, v121, v66
	v_exp_f32_e32 v125, v77
	v_add_f32_e32 v66, v73, v66
	v_exp_f32_e32 v126, v78
	v_add_f32_e32 v66, v122, v66
	v_exp_f32_e32 v127, v79
	v_add_f32_e32 v66, v123, v66
	v_add_f32_e32 v66, v124, v66
	v_add_f32_e32 v66, v125, v66
	v_add_f32_e32 v66, v126, v66
	v_add_f32_e32 v66, v127, v66
	v_add_f32_e32 v66, v128, v66
	v_add_f32_e32 v70, v129, v66
	v_mov_b32_e32 v72, v70
	s_nop 1
	v_permlane32_swap_b32_e32 v70, v72
	v_cvt_pk_bf16_f32 v66, v197, v199
	v_cvt_pk_bf16_f32 v67, v195, v198
	v_cvt_pk_bf16_f32 v68, v194, v196
	v_cvt_pk_bf16_f32 v69, v170, v171
	v_cvt_pk_bf16_f32 v74, v167, v169
	v_cvt_pk_bf16_f32 v75, v166, v168
	v_cvt_pk_bf16_f32 v76, v158, v165
	v_cvt_pk_bf16_f32 v77, v159, v164
	v_cvt_pk_bf16_f32 v78, v116, v117
	v_cvt_pk_bf16_f32 v79, v118, v119
	v_cvt_pk_bf16_f32 v80, v120, v71
	v_cvt_pk_bf16_f32 v81, v121, v73
	v_cvt_pk_bf16_f32 v116, v122, v123
	v_cvt_pk_bf16_f32 v117, v124, v125
	v_cvt_pk_bf16_f32 v118, v126, v127
	v_cvt_pk_bf16_f32 v119, v128, v129
	s_nop 0
	v_permlane32_swap_b32_e32 v66, v68
	v_permlane32_swap_b32_e32 v67, v69
	v_permlane32_swap_b32_e32 v74, v76
	v_permlane32_swap_b32_e32 v75, v77
	v_permlane32_swap_b32_e32 v78, v80
	v_permlane32_swap_b32_e32 v79, v81
	v_permlane32_swap_b32_e32 v116, v118
	v_permlane32_swap_b32_e32 v117, v119
	ds_read_b64_tr_b16 v[120:121], v179 offset:0
	ds_read_b64_tr_b16 v[122:123], v179 offset:0x800
	ds_read_b64_tr_b16 v[124:125], v179 offset:0x1000
	ds_read_b64_tr_b16 v[126:127], v179 offset:0x1800
	ds_read_b64_tr_b16 v[128:129], v179 offset:0x2000
	ds_read_b64_tr_b16 v[130:131], v179 offset:0x2800
	ds_read_b64_tr_b16 v[132:133], v179 offset:0x3000
	ds_read_b64_tr_b16 v[134:135], v179 offset:0x3800
	s_waitcnt lgkmcnt(0)
	s_nop 0
	v_mfma_f32_32x32x16_bf16 v[2:17], v[66:69], v[120:123], v[2:17]
	ds_read_b64_tr_b16 v[120:121], v179 offset:0x200
	ds_read_b64_tr_b16 v[122:123], v179 offset:0xa00
	v_mfma_f32_32x32x16_bf16 v[2:17], v[74:77], v[124:127], v[2:17]
	ds_read_b64_tr_b16 v[124:125], v179 offset:0x1200
	ds_read_b64_tr_b16 v[126:127], v179 offset:0x1a00
	v_mfma_f32_32x32x16_bf16 v[2:17], v[78:81], v[128:131], v[2:17]
	ds_read_b64_tr_b16 v[128:129], v179 offset:0x2200
	ds_read_b64_tr_b16 v[130:131], v179 offset:0x2a00
	v_mfma_f32_32x32x16_bf16 v[2:17], v[116:119], v[132:135], v[2:17]
	ds_read_b64_tr_b16 v[132:133], v179 offset:0x3200
	ds_read_b64_tr_b16 v[134:135], v179 offset:0x3a00
	s_waitcnt lgkmcnt(0)
	v_mfma_f32_32x32x16_bf16 v[18:33], v[66:69], v[120:123], v[18:33]
	ds_read_b64_tr_b16 v[120:121], v179 offset:0x400
	ds_read_b64_tr_b16 v[122:123], v179 offset:0xc00
	v_mfma_f32_32x32x16_bf16 v[18:33], v[74:77], v[124:127], v[18:33]
	ds_read_b64_tr_b16 v[124:125], v179 offset:0x1400
	ds_read_b64_tr_b16 v[126:127], v179 offset:0x1c00
	v_mfma_f32_32x32x16_bf16 v[18:33], v[78:81], v[128:131], v[18:33]
	ds_read_b64_tr_b16 v[128:129], v179 offset:0x2400
	ds_read_b64_tr_b16 v[130:131], v179 offset:0x2c00
	v_mfma_f32_32x32x16_bf16 v[18:33], v[116:119], v[132:135], v[18:33]
	ds_read_b64_tr_b16 v[132:133], v179 offset:0x3400
	ds_read_b64_tr_b16 v[134:135], v179 offset:0x3c00
	s_waitcnt lgkmcnt(0)
	v_mfma_f32_32x32x16_bf16 v[34:49], v[66:69], v[120:123], v[34:49]
	ds_read_b64_tr_b16 v[120:121], v179 offset:0x600
	ds_read_b64_tr_b16 v[122:123], v179 offset:0xe00
	v_mfma_f32_32x32x16_bf16 v[34:49], v[74:77], v[124:127], v[34:49]
	ds_read_b64_tr_b16 v[124:125], v179 offset:0x1600
	ds_read_b64_tr_b16 v[126:127], v179 offset:0x1e00
	v_mfma_f32_32x32x16_bf16 v[34:49], v[78:81], v[128:131], v[34:49]
	ds_read_b64_tr_b16 v[128:129], v179 offset:0x2600
	ds_read_b64_tr_b16 v[130:131], v179 offset:0x2e00
	v_mfma_f32_32x32x16_bf16 v[34:49], v[116:119], v[132:135], v[34:49]
	ds_read_b64_tr_b16 v[132:133], v179 offset:0x3600
	ds_read_b64_tr_b16 v[134:135], v179 offset:0x3e00
	s_waitcnt lgkmcnt(0)
	v_mfma_f32_32x32x16_bf16 v[50:65], v[66:69], v[120:123], v[50:65]
	v_exp_f32_e32 v66, v98
	v_exp_f32_e32 v67, v99
	v_exp_f32_e32 v68, v100
	v_exp_f32_e32 v69, v101
	v_add_f32_e32 v71, 0, v66
	v_add_f32_e32 v71, v67, v71
	v_add_f32_e32 v71, v68, v71
	v_mfma_f32_32x32x16_bf16 v[50:65], v[74:77], v[124:127], v[50:65]
	v_exp_f32_e32 v74, v102
	v_exp_f32_e32 v75, v103
	v_exp_f32_e32 v76, v104
	v_exp_f32_e32 v77, v105
	v_add_f32_e32 v71, v69, v71
	v_add_f32_e32 v71, v74, v71
	v_add_f32_e32 v71, v75, v71
	v_mfma_f32_32x32x16_bf16 v[50:65], v[78:81], v[128:131], v[50:65]
	v_exp_f32_e32 v78, v106
	v_exp_f32_e32 v79, v107
	v_exp_f32_e32 v80, v108
	v_add_f32_e32 v71, v76, v71
	v_exp_f32_e32 v81, v109
	v_add_f32_e32 v71, v77, v71
	v_exp_f32_e32 v98, v110
	v_add_f32_e32 v71, v78, v71
	v_exp_f32_e32 v99, v111
	v_add_f32_e32 v71, v79, v71
	v_exp_f32_e32 v100, v112
	v_add_f32_e32 v71, v80, v71
	v_exp_f32_e32 v101, v113
	v_add_f32_e32 v71, v81, v71
	v_exp_f32_e32 v82, v82
	v_add_f32_e32 v71, v98, v71
	v_exp_f32_e32 v83, v83
	v_add_f32_e32 v71, v99, v71
	v_exp_f32_e32 v84, v84
	v_add_f32_e32 v71, v100, v71
	v_exp_f32_e32 v85, v85
	v_add_f32_e32 v71, v101, v71
	v_exp_f32_e32 v86, v86
	v_add_f32_e32 v71, v82, v71
	v_exp_f32_e32 v87, v87
	v_add_f32_e32 v71, v83, v71
	v_exp_f32_e32 v88, v88
	v_add_f32_e32 v71, v84, v71
	v_exp_f32_e32 v89, v89
	v_add_f32_e32 v71, v85, v71
	v_exp_f32_e32 v90, v90
	v_add_f32_e32 v71, v86, v71
	v_exp_f32_e32 v91, v91
	v_add_f32_e32 v71, v87, v71
	v_exp_f32_e32 v92, v92
	v_add_f32_e32 v71, v88, v71
	v_exp_f32_e32 v93, v93
	v_add_f32_e32 v71, v89, v71
	v_exp_f32_e32 v94, v94
	v_add_f32_e32 v71, v90, v71
	v_exp_f32_e32 v95, v95
	v_add_f32_e32 v71, v91, v71
	v_mfma_f32_32x32x16_bf16 v[50:65], v[116:119], v[132:135], v[50:65]
	v_exp_f32_e32 v96, v96
	v_add_f32_e32 v71, v92, v71
	v_exp_f32_e32 v97, v97
	v_add_f32_e32 v71, v93, v71
	v_add_f32_e32 v71, v94, v71
	v_add_f32_e32 v71, v95, v71
	v_add_f32_e32 v71, v96, v71
	v_add_f32_e32 v71, v97, v71
	v_mov_b32_e32 v73, v71
	s_barrier
	s_nop 0
	v_permlane32_swap_b32_e32 v71, v73
	v_cvt_pk_bf16_f32 v66, v66, v67
	v_cvt_pk_bf16_f32 v67, v68, v69
	v_cvt_pk_bf16_f32 v68, v74, v75
	v_cvt_pk_bf16_f32 v69, v76, v77
	v_cvt_pk_bf16_f32 v74, v78, v79
	v_cvt_pk_bf16_f32 v75, v80, v81
	v_cvt_pk_bf16_f32 v76, v98, v99
	v_cvt_pk_bf16_f32 v77, v100, v101
	v_cvt_pk_bf16_f32 v78, v82, v83
	v_cvt_pk_bf16_f32 v79, v84, v85
	v_cvt_pk_bf16_f32 v80, v86, v87
	v_cvt_pk_bf16_f32 v81, v88, v89
	v_cvt_pk_bf16_f32 v82, v90, v91
	v_cvt_pk_bf16_f32 v83, v92, v93
	v_cvt_pk_bf16_f32 v84, v94, v95
	v_cvt_pk_bf16_f32 v85, v96, v97
	s_nop 0
	v_permlane32_swap_b32_e32 v66, v68
	v_permlane32_swap_b32_e32 v67, v69
	v_permlane32_swap_b32_e32 v74, v76
	v_permlane32_swap_b32_e32 v75, v77
	v_permlane32_swap_b32_e32 v78, v80
	v_permlane32_swap_b32_e32 v79, v81
	v_permlane32_swap_b32_e32 v82, v84
	v_permlane32_swap_b32_e32 v83, v85
	ds_read_b64_tr_b16 v[86:87], v176 offset:0
	ds_read_b64_tr_b16 v[88:89], v176 offset:0x800
	ds_read_b64_tr_b16 v[90:91], v176 offset:0x1000
	ds_read_b64_tr_b16 v[92:93], v176 offset:0x1800
	ds_read_b64_tr_b16 v[94:95], v176 offset:0x2000
	ds_read_b64_tr_b16 v[96:97], v176 offset:0x2800
	ds_read_b64_tr_b16 v[98:99], v176 offset:0x3000
	ds_read_b64_tr_b16 v[100:101], v176 offset:0x3800
	s_waitcnt lgkmcnt(0)
	s_nop 0
	v_mfma_f32_32x32x16_bf16 v[2:17], v[66:69], v[86:89], v[2:17]
	ds_read_b64_tr_b16 v[86:87], v176 offset:0x200
	ds_read_b64_tr_b16 v[88:89], v176 offset:0xa00
	v_mfma_f32_32x32x16_bf16 v[2:17], v[74:77], v[90:93], v[2:17]
	ds_read_b64_tr_b16 v[90:91], v176 offset:0x1200
	ds_read_b64_tr_b16 v[92:93], v176 offset:0x1a00
	v_mfma_f32_32x32x16_bf16 v[2:17], v[78:81], v[94:97], v[2:17]
	ds_read_b64_tr_b16 v[94:95], v176 offset:0x2200
	ds_read_b64_tr_b16 v[96:97], v176 offset:0x2a00
	v_mfma_f32_32x32x16_bf16 v[2:17], v[82:85], v[98:101], v[2:17]
	ds_read_b64_tr_b16 v[98:99], v176 offset:0x3200
	ds_read_b64_tr_b16 v[100:101], v176 offset:0x3a00
	s_waitcnt lgkmcnt(0)
	v_mfma_f32_32x32x16_bf16 v[18:33], v[66:69], v[86:89], v[18:33]
	ds_read_b64_tr_b16 v[86:87], v176 offset:0x400
	ds_read_b64_tr_b16 v[88:89], v176 offset:0xc00
	v_mfma_f32_32x32x16_bf16 v[18:33], v[74:77], v[90:93], v[18:33]
	ds_read_b64_tr_b16 v[90:91], v176 offset:0x1400
	ds_read_b64_tr_b16 v[92:93], v176 offset:0x1c00
	v_mfma_f32_32x32x16_bf16 v[18:33], v[78:81], v[94:97], v[18:33]
	ds_read_b64_tr_b16 v[94:95], v176 offset:0x2400
	ds_read_b64_tr_b16 v[96:97], v176 offset:0x2c00
	v_mfma_f32_32x32x16_bf16 v[18:33], v[82:85], v[98:101], v[18:33]
	ds_read_b64_tr_b16 v[98:99], v176 offset:0x3400
	ds_read_b64_tr_b16 v[100:101], v176 offset:0x3c00
	s_waitcnt lgkmcnt(0)
	v_mfma_f32_32x32x16_bf16 v[34:49], v[66:69], v[86:89], v[34:49]
	ds_read_b64_tr_b16 v[86:87], v176 offset:0x600
	ds_read_b64_tr_b16 v[88:89], v176 offset:0xe00
	v_mfma_f32_32x32x16_bf16 v[34:49], v[74:77], v[90:93], v[34:49]
	ds_read_b64_tr_b16 v[90:91], v176 offset:0x1600
	ds_read_b64_tr_b16 v[92:93], v176 offset:0x1e00
	v_mfma_f32_32x32x16_bf16 v[34:49], v[78:81], v[94:97], v[34:49]
	ds_read_b64_tr_b16 v[94:95], v176 offset:0x2600
	ds_read_b64_tr_b16 v[96:97], v176 offset:0x2e00
	v_mfma_f32_32x32x16_bf16 v[34:49], v[82:85], v[98:101], v[34:49]
	ds_read_b64_tr_b16 v[98:99], v176 offset:0x3600
	ds_read_b64_tr_b16 v[100:101], v176 offset:0x3e00
	s_waitcnt lgkmcnt(0)
	v_mfma_f32_32x32x16_bf16 v[50:65], v[66:69], v[86:89], v[50:65]
	v_cmp_gt_u32_e32 vcc, 32, v114
	v_mfma_f32_32x32x16_bf16 v[50:65], v[74:77], v[90:93], v[50:65]
	v_mfma_f32_32x32x16_bf16 v[50:65], v[78:81], v[94:97], v[50:65]
	v_mfma_f32_32x32x16_bf16 v[50:65], v[82:85], v[98:101], v[50:65]
	s_and_saveexec_b64 s[0:1], vcc
	s_cbranch_execz .LBB0_778
	v_pk_add_f32 v[66:67], v[70:71], v[72:73]
	v_lshl_add_u32 v68, v173, 2, v148
	v_add_f32_e32 v66, v180, v66
	v_add_f32_e32 v66, v66, v67
	ds_write_b32 v68, v66
	s_branch .LBB0_778
